# scan: log-sigmoid/gamma math overlapped with the 16 tile loads (counted vmcnt, full wait moved to first use of tile data); r2 units: wave-uniform decay logits fetched with s_load instead of a vector l
# baseline (speedup 1.0000x reference)
; __device__ __forceinline__ void ret_gammas(const Args& a, int l, int h, float& lgf2, float& lgb2) {
;     const float xf = a.in[8][(l * 2 + 0) * 4 + h], xb = a.in[8][(l * 2 + 1) * 4 + h];
;     lgf2 = -log1pf(expf(-xf)) * LOG2E; lgb2 = -log1pf(expf(-xb)) * LOG2E;
; __device__ __forceinline__ void phase_scan(const Args& a, unsigned char* ws, bf16* STB, int l, int vcu, int G, int tid, int z) {
;     ...
;     for (int it = gt; it < 192 * 2 * 2048; it += NT) {
;         const int grp = it & 2047, dir = (it >> 11) & 1, bh = it >> 12, h = bh & 3;
;         float lgf2, lgb2; ret_gammas(a, l, h, lgf2, lgb2);
;         const float g = __builtin_amdgcn_exp2f(128.f * (dir ? lgb2 : lgf2));
;         bf16* base = ST + ((size_t)(bh * 16) * 2 + dir) * 16384 + grp * 8;
;         u32x4 kv[16];
;         const size_t cst = (size_t)(32768 + z);
; #pragma unroll
;         for (int n = 0; n < 16; ++n) kv[n] = *(const u32x4*)(base + (size_t)n * cst);
.LBB0_564:
	v_ashrrev_i32_e32 v1, 12, v74
	v_lshlrev_b32_e32 v3, 2, v1
	v_and_b32_e32 v3, 12, v3
	global_load_dword v67, v3, s[6:7]
	global_load_dword v79, v3, s[6:7] offset:16
	v_lshlrev_b32_e32 v4, 4, v1
	v_ashrrev_i32_e32 v5, 31, v4
	v_bfe_u32 v78, v74, 11, 1
	v_lshlrev_b64 v[4:5], 16, v[4:5]
	v_and_b32_e32 v2, 0x3ff8, v75
	v_lshlrev_b32_e32 v64, 15, v78
	v_lshl_add_u64 v[4:5], s[8:9], 0, v[4:5]
	v_lshl_add_u64 v[4:5], v[4:5], 0, v[64:65]
	v_lshlrev_b32_e32 v64, 1, v2
	v_lshl_add_u64 v[72:73], v[4:5], 0, v[64:65]
	v_lshl_add_u64 v[4:5], s[10:11], 1, v[72:73]
	v_lshl_add_u64 v[12:13], v[4:5], 0, s[12:13]
	v_bfe_i32 v0, v74, 11, 1
	v_lshl_add_u64 v[14:15], v[12:13], 0, s[12:13]
	v_and_b32_e32 v0, 15, v0
	v_add_u32_e32 v6, 7, v78
	v_sub_u32_e32 v8, 8, v78
	v_lshl_add_u64 v[16:17], v[14:15], 0, s[12:13]
	v_mad_i64_i32 v[0:1], s[2:3], v0, s10, 0
	v_mad_i64_i32 v[6:7], s[2:3], v6, s10, 0
	v_mad_i64_i32 v[8:9], s[2:3], v8, s10, 0
	v_lshl_add_u64 v[18:19], v[16:17], 0, s[12:13]
	v_lshl_add_u64 v[84:85], v[0:1], 1, v[72:73]
	v_lshl_add_u64 v[70:71], v[6:7], 1, v[72:73]
	v_lshl_add_u64 v[68:69], v[8:9], 1, v[72:73]
	global_load_dwordx4 v[56:59], v[72:73], off
	global_load_dwordx4 v[0:3], v[4:5], off
	s_nop 0
	global_load_dwordx4 v[4:7], v[12:13], off
	global_load_dwordx4 v[8:11], v[14:15], off
	s_nop 0
	global_load_dwordx4 v[12:15], v[16:17], off
	global_load_dwordx4 v[20:23], v[18:19], off
	v_lshl_add_u64 v[16:17], v[18:19], 0, s[12:13]
	global_load_dwordx4 v[32:35], v[16:17], off
	v_lshl_add_u64 v[16:17], v[16:17], 0, s[12:13]
	global_load_dwordx4 v[48:51], v[16:17], off
	v_lshl_add_u64 v[16:17], v[16:17], 0, s[12:13]
	global_load_dwordx4 v[52:55], v[16:17], off
	v_lshl_add_u64 v[16:17], v[16:17], 0, s[12:13]
	global_load_dwordx4 v[44:47], v[16:17], off
	v_lshl_add_u64 v[16:17], v[16:17], 0, s[12:13]
	global_load_dwordx4 v[40:43], v[16:17], off
	v_lshl_add_u64 v[16:17], v[16:17], 0, s[12:13]
	global_load_dwordx4 v[36:39], v[16:17], off
	v_lshl_add_u64 v[16:17], v[16:17], 0, s[12:13]
	global_load_dwordx4 v[28:31], v[16:17], off
	v_lshl_add_u64 v[16:17], v[16:17], 0, s[12:13]
	v_lshl_add_u64 v[60:61], v[16:17], 0, s[12:13]
	global_load_dwordx4 v[24:27], v[16:17], off
	v_add_u32_e32 v74, s0, v74
	global_load_dwordx4 v[16:19], v[60:61], off
	v_lshl_add_u64 v[60:61], v[60:61], 0, s[12:13]
	global_load_dwordx4 v[60:63], v[60:61], off
	v_cmp_lt_i32_e32 vcc, s23, v74
	global_store_dwordx4 v[84:85], v[80:83], off
	s_or_b64 s[14:15], vcc, s[14:15]
	v_add_u32_e32 v75, s1, v75
	s_waitcnt vmcnt(17)
	v_mul_f32_e32 v64, 0xbfb8aa3b, v67
	v_mul_f32_e32 v84, 0xbfb8aa3b, v79
	v_fma_f32 v85, v67, s16, -v64
	v_rndne_f32_e32 v86, v64
	v_fma_f32 v87, v79, s16, -v84
	v_rndne_f32_e32 v88, v84
	v_fmac_f32_e32 v85, 0xb2a5705f, v67
	v_sub_f32_e32 v64, v64, v86
	v_fmac_f32_e32 v87, 0xb2a5705f, v79
	v_sub_f32_e32 v84, v84, v88
	v_add_f32_e32 v64, v64, v85
	v_cvt_i32_f32_e32 v86, v86
	v_add_f32_e32 v84, v84, v87
	v_exp_f32_e32 v64, v64
	v_cvt_i32_f32_e32 v88, v88
	v_exp_f32_e32 v84, v84
	v_cmp_nlt_f32_e64 s[2:3], s17, v67
	v_ldexp_f32 v64, v64, v86
	v_cmp_nlt_f32_e32 vcc, s17, v79
	v_ldexp_f32 v84, v84, v88
	v_cndmask_b32_e64 v64, 0, v64, s[2:3]
	v_cmp_ngt_f32_e64 s[2:3], s18, v67
	v_cndmask_b32_e32 v84, 0, v84, vcc
	v_cmp_ngt_f32_e32 vcc, s18, v79
	v_cndmask_b32_e64 v64, v76, v64, s[2:3]
	v_add_f32_e32 v67, 1.0, v64
	v_cndmask_b32_e32 v79, v76, v84, vcc
	v_add_f32_e32 v88, 1.0, v79
	v_add_f32_e32 v89, -1.0, v67
	v_frexp_mant_f32_e32 v90, v67
	v_cvt_f64_f32_e32 v[84:85], v67
	v_add_f32_e32 v91, -1.0, v88
	v_frexp_mant_f32_e32 v92, v88
	v_cvt_f64_f32_e32 v[86:87], v88
	v_sub_f32_e32 v93, v89, v67
	v_frexp_exp_i32_f64_e32 v84, v[84:85]
	v_cmp_gt_f32_e32 vcc, s20, v90
	v_sub_f32_e32 v89, v64, v89
	v_sub_f32_e32 v85, v91, v88
	v_frexp_exp_i32_f64_e32 v86, v[86:87]
	v_cmp_gt_f32_e64 s[2:3], s20, v92
	v_add_f32_e32 v87, 1.0, v93
	v_subbrev_co_u32_e32 v84, vcc, 0, v84, vcc
	v_sub_f32_e32 v90, v79, v91
	v_add_f32_e32 v85, 1.0, v85
	v_subbrev_co_u32_e64 v86, vcc, 0, v86, s[2:3]
	v_add_f32_e32 v87, v89, v87
	v_sub_u32_e32 v89, 0, v84
	v_add_f32_e32 v85, v90, v85
	v_sub_u32_e32 v90, 0, v86
	v_ldexp_f32 v67, v67, v89
	v_ldexp_f32 v88, v88, v90
	v_ldexp_f32 v85, v85, v90
	v_add_f32_e32 v90, -1.0, v67
	v_add_f32_e32 v92, 1.0, v67
	v_ldexp_f32 v87, v87, v89
	v_add_f32_e32 v93, -1.0, v88
	v_add_f32_e32 v94, 1.0, v88
	v_add_f32_e32 v89, 1.0, v90
	v_add_f32_e32 v91, -1.0, v92
	v_add_f32_e32 v95, 1.0, v93
	v_add_f32_e32 v96, -1.0, v94
	v_sub_f32_e32 v89, v67, v89
	v_sub_f32_e32 v67, v67, v91
	v_sub_f32_e32 v91, v88, v95
	v_sub_f32_e32 v88, v88, v96
	v_add_f32_e32 v67, v87, v67
	v_add_f32_e32 v95, v87, v89
	v_add_f32_e32 v87, v85, v91
	v_add_f32_e32 v85, v85, v88
	v_add_f32_e32 v100, v92, v67
	v_add_f32_e32 v101, v94, v85
	v_rcp_f32_e32 v102, v100
	v_rcp_f32_e32 v103, v101
	v_add_f32_e32 v89, v90, v95
	v_add_f32_e32 v91, v93, v87
	v_sub_f32_e32 v88, v92, v100
	v_sub_f32_e32 v92, v94, v101
	v_mul_f32_e32 v105, v89, v102
	v_add_f32_e32 v85, v85, v92
	v_mul_f32_e32 v106, v91, v103
	v_mul_f32_e32 v92, v100, v105
	v_add_f32_e32 v67, v67, v88
	v_mul_f32_e32 v94, v101, v106
	v_fma_f32 v96, v105, v100, -v92
	v_fma_f32 v98, v106, v101, -v94
	v_fmac_f32_e32 v96, v105, v67
	v_sub_f32_e32 v90, v90, v89
	v_sub_f32_e32 v93, v93, v91
	v_fmac_f32_e32 v98, v106, v85
	v_add_f32_e32 v88, v92, v96
	v_add_f32_e32 v104, v95, v90
	v_add_f32_e32 v87, v87, v93
	v_add_f32_e32 v90, v94, v98
	v_sub_f32_e32 v93, v89, v88
	v_mov_b32_e32 v97, v88
	v_sub_f32_e32 v95, v91, v90
	v_pk_add_f32 v[88:89], v[88:89], v[92:93] neg_lo:[0,1] neg_hi:[0,1]
	v_mov_b32_e32 v99, v90
	v_pk_add_f32 v[90:91], v[90:91], v[94:95] neg_lo:[0,1] neg_hi:[0,1]
; __device__ __forceinline__ void ret_gammas(const Args& a, int l, int h, float& lgf2, float& lgb2) {
;     const float xf = a.in[8][(l * 2 + 0) * 4 + h], xb = a.in[8][(l * 2 + 1) * 4 + h];
;     lgf2 = -log1pf(expf(-xf)) * LOG2E; lgb2 = -log1pf(expf(-xb)) * LOG2E;
; __device__ __forceinline__ void phase_scan(const Args& a, unsigned char* ws, bf16* STB, int l, int vcu, int G, int tid, int z) {
;     ...
;         float lgf2, lgb2; ret_gammas(a, l, h, lgf2, lgb2);
;         const float g = __builtin_amdgcn_exp2f(128.f * (dir ? lgb2 : lgf2));
	v_pk_add_f32 v[88:89], v[88:89], v[96:97] neg_lo:[0,1] neg_hi:[0,1]
	v_pk_add_f32 v[90:91], v[90:91], v[98:99] neg_lo:[0,1] neg_hi:[0,1]
	v_add_f32_e32 v89, v104, v89
	v_add_f32_e32 v87, v87, v91
	v_add_f32_e32 v88, v88, v89
	v_add_f32_e32 v87, v90, v87
	v_add_f32_e32 v89, v93, v88
	v_add_f32_e32 v91, v95, v87
	v_mul_f32_e32 v90, v102, v89
	v_mul_f32_e32 v97, v103, v91
	v_mul_f32_e32 v92, v100, v90
	v_sub_f32_e32 v93, v93, v89
	v_add_f32_e32 v107, v105, v90
	v_mul_f32_e32 v94, v101, v97
	v_fma_f32 v96, v90, v100, -v92
	v_add_f32_e32 v104, v88, v93
	v_add_f32_e32 v108, v106, v97
	v_sub_f32_e32 v88, v107, v105
	v_fma_f32 v98, v97, v101, -v94
	v_fmac_f32_e32 v96, v90, v67
	v_sub_f32_e32 v93, v108, v106
	v_sub_f32_e32 v67, v90, v88
	v_fmac_f32_e32 v98, v97, v85
	v_add_f32_e32 v88, v92, v96
	v_sub_f32_e32 v95, v95, v91
	v_sub_f32_e32 v85, v97, v93
	v_add_f32_e32 v90, v94, v98
	v_sub_f32_e32 v93, v89, v88
	v_add_f32_e32 v87, v87, v95
	v_mov_b32_e32 v97, v88
	v_sub_f32_e32 v95, v91, v90
	v_pk_add_f32 v[88:89], v[88:89], v[92:93] neg_lo:[0,1] neg_hi:[0,1]
	v_mov_b32_e32 v99, v90
	v_pk_add_f32 v[90:91], v[90:91], v[94:95] neg_lo:[0,1] neg_hi:[0,1]
	v_pk_add_f32 v[88:89], v[88:89], v[96:97] neg_lo:[0,1] neg_hi:[0,1]
	v_pk_add_f32 v[90:91], v[90:91], v[98:99] neg_lo:[0,1] neg_hi:[0,1]
	v_add_f32_e32 v89, v104, v89
	v_add_f32_e32 v87, v87, v91
	v_add_f32_e32 v88, v88, v89
	v_add_f32_e32 v87, v90, v87
	v_add_f32_e32 v88, v93, v88
	v_add_f32_e32 v87, v95, v87
	v_mul_f32_e32 v88, v102, v88
	v_mul_f32_e32 v87, v103, v87
	v_add_f32_e32 v67, v67, v88
	v_cvt_f32_i32_e32 v84, v84
	v_add_f32_e32 v87, v85, v87
	v_add_f32_e32 v85, v107, v67
	v_cvt_f32_i32_e32 v86, v86
	v_add_f32_e32 v88, v108, v87
	v_mul_f32_e32 v90, v85, v85
	v_sub_f32_e32 v92, v85, v107
	v_mul_f32_e32 v94, v88, v88
	v_sub_f32_e32 v93, v88, v108
	v_fmamk_f32 v95, v90, 0x3e9b6dac, v77
	v_ldexp_f32 v89, v85, 1
	v_sub_f32_e32 v92, v67, v92
	v_mul_f32_e32 v85, v85, v90
	v_fmamk_f32 v96, v94, 0x3e9b6dac, v77
	v_sub_f32_e32 v93, v87, v93
	v_fmaak_f32 v67, v90, v95, 0x3f2aaada
	v_mul_f32_e32 v87, v88, v94
	v_ldexp_f32 v95, v92, 1
	v_ldexp_f32 v104, v93, 1
	v_pk_mul_f32 v[92:93], v[84:85], v[66:67]
	v_fmaak_f32 v67, v94, v96, 0x3f2aaada
	v_ldexp_f32 v91, v88, 1
	v_fma_f32 v88, v84, s21, -v92
	v_pk_mul_f32 v[96:97], v[86:87], v[66:67]
	v_fmac_f32_e32 v88, 0xb102e308, v84
	v_fma_f32 v90, v86, s21, -v96
	v_pk_add_f32 v[98:99], v[92:93], v[88:89]
	v_fmac_f32_e32 v90, 0xb102e308, v86
	v_sub_f32_e32 v67, v99, v89
	v_pk_add_f32 v[102:103], v[96:97], v[90:91]
	v_sub_f32_e32 v67, v93, v67
	v_sub_f32_e32 v85, v103, v91
	v_mov_b32_e32 v94, v92
	v_add_f32_e32 v95, v95, v67
	v_sub_f32_e32 v67, v97, v85
	v_mov_b32_e32 v84, v96
	v_pk_add_f32 v[86:87], v[98:99], v[92:93] neg_lo:[0,1] neg_hi:[0,1]
	v_pk_add_f32 v[92:93], v[102:103], v[96:97] neg_lo:[0,1] neg_hi:[0,1]
	v_pk_add_f32 v[96:97], v[98:99], v[94:95]
	v_add_f32_e32 v85, v104, v67
	v_mov_b32_e32 v89, v98
	v_mov_b32_e32 v87, v97
	v_pk_add_f32 v[106:107], v[102:103], v[84:85]
	v_mov_b32_e32 v91, v102
	v_mov_b32_e32 v104, v85
	v_pk_add_f32 v[84:85], v[88:89], v[86:87] neg_lo:[0,1] neg_hi:[0,1]
	v_pk_add_f32 v[86:87], v[88:89], v[86:87]
	v_mov_b32_e32 v93, v107
	v_pk_add_f32 v[108:109], v[86:87], v[98:99] op_sel:[1,0] op_sel_hi:[0,1] neg_lo:[0,1] neg_hi:[0,1]
	v_pk_add_f32 v[110:111], v[90:91], v[92:93] neg_lo:[0,1] neg_hi:[0,1]
	v_pk_add_f32 v[90:91], v[90:91], v[92:93]
	v_mov_b32_e32 v101, v98
	v_mov_b32_e32 v100, v95
	v_mov_b32_e32 v94, v97
	v_mov_b32_e32 v95, v87
	v_pk_add_f32 v[92:93], v[96:97], v[108:109] op_sel_hi:[1,0] neg_lo:[0,1] neg_hi:[0,1]
	v_pk_mov_b32 v[96:97], v[98:99], v[108:109] op_sel:[1,0]
	v_pk_add_f32 v[98:99], v[90:91], v[102:103] op_sel:[1,0] op_sel_hi:[0,1] neg_lo:[0,1] neg_hi:[0,1]
	v_mov_b32_e32 v88, v107
	v_mov_b32_e32 v89, v91
	v_pk_add_f32 v[94:95], v[94:95], v[96:97] neg_lo:[0,1] neg_hi:[0,1]
	v_pk_add_f32 v[96:97], v[106:107], v[98:99] op_sel_hi:[1,0] neg_lo:[0,1] neg_hi:[0,1]
	v_pk_mov_b32 v[98:99], v[102:103], v[98:99] op_sel:[1,0]
	v_mov_b32_e32 v105, v102
	v_mov_b32_e32 v92, v84
	v_pk_add_f32 v[94:95], v[100:101], v[94:95] neg_lo:[0,1] neg_hi:[0,1]
	v_pk_add_f32 v[88:89], v[88:89], v[98:99] neg_lo:[0,1] neg_hi:[0,1]
	v_mov_b32_e32 v96, v110
	v_pk_add_f32 v[92:93], v[92:93], v[94:95]
	v_pk_add_f32 v[88:89], v[104:105], v[88:89] neg_lo:[0,1] neg_hi:[0,1]
	v_pk_add_f32 v[98:99], v[92:93], v[92:93] op_sel:[0,1] op_sel_hi:[1,0]
	v_pk_add_f32 v[96:97], v[96:97], v[88:89]
	v_mov_b32_e32 v85, v87
	v_pk_add_f32 v[86:87], v[86:87], v[98:99] op_sel:[1,0] op_sel_hi:[0,1]
	v_mov_b32_e32 v95, v98
	v_pk_add_f32 v[98:99], v[96:97], v[96:97] op_sel:[0,1] op_sel_hi:[1,0]
	v_mov_b32_e32 v111, v91
	v_mov_b32_e32 v93, v86
	v_pk_add_f32 v[90:91], v[90:91], v[98:99] op_sel:[1,0] op_sel_hi:[0,1]
	v_mov_b32_e32 v89, v98
	v_pk_add_f32 v[98:99], v[92:93], v[84:85] neg_lo:[0,1] neg_hi:[0,1]
	v_mov_b32_e32 v97, v90
	v_sub_f32_e32 v67, v92, v98
	v_pk_add_f32 v[92:93], v[96:97], v[110:111] neg_lo:[0,1] neg_hi:[0,1]
	v_pk_add_f32 v[94:95], v[94:95], v[98:99] neg_lo:[0,1] neg_hi:[0,1]
	v_sub_f32_e32 v67, v84, v67
	v_sub_f32_e32 v87, v96, v92
	v_pk_add_f32 v[84:85], v[88:89], v[92:93] neg_lo:[0,1] neg_hi:[0,1]
	v_add_f32_e32 v67, v94, v67
	v_sub_f32_e32 v87, v110, v87
	v_add_f32_e32 v67, v67, v95
	v_add_f32_e32 v84, v84, v87
	v_add_f32_e32 v67, v86, v67
	v_add_f32_e32 v84, v84, v85
	v_cmp_neq_f32_e32 vcc, s19, v64
	v_add_f32_e32 v84, v90, v84
	v_cmp_lt_f32_e64 s[2:3], |v64|, s22
	v_cndmask_b32_e32 v67, v76, v67, vcc
	v_cmp_neq_f32_e32 vcc, s19, v79
	v_cndmask_b32_e64 v64, v67, v64, s[2:3]
	s_nop 0
	v_cndmask_b32_e32 v67, v76, v84, vcc
	v_cmp_lt_f32_e64 vcc, |v79|, s22
	s_nop 1
	v_cndmask_b32_e32 v67, v67, v79, vcc
	v_cmp_eq_u32_e32 vcc, 0, v78
	s_nop 1
	v_cndmask_b32_e32 v64, v67, v64, vcc
	v_mul_f32_e32 v64, 0xbfb8aa3b, v64
	v_mul_f32_e32 v64, 0x43000000, v64
	v_exp_f32_e32 v64, v64
	s_waitcnt vmcnt(0)
; __device__ __forceinline__ unsigned pkbf(float lo, float hi) { typedef __bf16 bf2_t __attribute__((ext_vector_type(2))); f32x2 v = {lo, hi}; bf2_t b = __builtin_convertvector(v, bf2_t); return __builtin_bit_cast(unsigned, b); }
; __device__ __forceinline__ void phase_scan(const Args& a, unsigned char* ws, bf16* STB, int l, int vcu, int G, int tid, int z) {
;     ...
;         for (int i = 0; i < 16; ++i) {
;             const int n = dir ? 15 - i : i;
;             u32x4 w; w.x = pkbf(c[0], c[1]); w.y = pkbf(c[2], c[3]); w.z = pkbf(c[4], c[5]); w.w = pkbf(c[6], c[7]);
;             *(u32x4*)(base + (size_t)n * cst) = w;
; #pragma unroll
;             for (int e = 0; e < 4; ++e) { c[2 * e] = bflo(kv[n][e]) + g * c[2 * e]; c[2 * e + 1] = bfhi(kv[n][e]) + g * c[2 * e + 1]; }
	v_cndmask_b32_e32 v59, v63, v59, vcc
	v_cndmask_b32_e32 v58, v62, v58, vcc
	v_cndmask_b32_e32 v57, v61, v57, vcc
	v_cndmask_b32_e32 v56, v60, v56, vcc
	v_cndmask_b32_e64 v60, 14, 1, vcc
	v_cndmask_b32_e32 v61, v19, v3, vcc
	v_cndmask_b32_e32 v62, v18, v2, vcc
	v_cndmask_b32_e32 v63, v17, v1, vcc
	v_cndmask_b32_e64 v78, 13, 2, vcc
	v_cndmask_b32_e32 v79, v27, v7, vcc
	v_cndmask_b32_e32 v84, v26, v6, vcc
	v_cndmask_b32_e32 v85, v25, v5, vcc
	v_cndmask_b32_e32 v86, v24, v4, vcc
	v_cndmask_b32_e64 v87, 12, 3, vcc
	v_cndmask_b32_e32 v88, v31, v11, vcc
	v_cndmask_b32_e32 v89, v30, v10, vcc
	v_cndmask_b32_e32 v90, v29, v9, vcc
	v_cndmask_b32_e32 v91, v28, v8, vcc
	v_cndmask_b32_e64 v92, 11, 4, vcc
	v_cndmask_b32_e32 v93, v39, v15, vcc
	v_cndmask_b32_e32 v96, v36, v12, vcc
	v_cndmask_b32_e64 v97, 10, 5, vcc
	v_cndmask_b32_e32 v98, v43, v23, vcc
	v_cndmask_b32_e32 v99, v42, v22, vcc
	v_cndmask_b32_e32 v100, v41, v21, vcc
	v_cndmask_b32_e32 v101, v40, v20, vcc
	v_cndmask_b32_e64 v102, 9, 6, vcc
	v_cndmask_b32_e32 v103, v47, v35, vcc
	v_cndmask_b32_e32 v104, v46, v34, vcc
	v_cndmask_b32_e32 v105, v45, v33, vcc
	v_cndmask_b32_e32 v106, v44, v32, vcc
	v_cndmask_b32_e32 v107, v55, v51, vcc
	v_cndmask_b32_e32 v108, v54, v50, vcc
	v_cndmask_b32_e32 v109, v53, v49, vcc
	v_cndmask_b32_e32 v110, v52, v48, vcc
	v_cndmask_b32_e32 v111, v51, v55, vcc
	v_cndmask_b32_e32 v112, v50, v54, vcc
	v_cndmask_b32_e32 v113, v49, v53, vcc
	v_cndmask_b32_e64 v115, 6, 9, vcc
	v_cndmask_b32_e32 v116, v35, v47, vcc
	v_cndmask_b32_e32 v117, v34, v46, vcc
	v_cndmask_b32_e32 v118, v33, v45, vcc
	v_cndmask_b32_e32 v119, v32, v44, vcc
	v_cndmask_b32_e64 v120, 5, 10, vcc
	v_cndmask_b32_e32 v122, v22, v42, vcc
	v_cndmask_b32_e32 v123, v21, v41, vcc
	v_cndmask_b32_e64 v125, 4, 11, vcc
	v_cndmask_b32_e64 v132, 3, 12, vcc
	v_cndmask_b32_e64 v142, 2, 13, vcc
	v_cndmask_b32_e64 v152, 1, 14, vcc
	v_cndmask_b32_e64 v162, 0, 15, vcc
	v_cndmask_b32_e32 v67, v16, v0, vcc
	v_cndmask_b32_e32 v94, v38, v14, vcc
	v_cndmask_b32_e32 v95, v37, v13, vcc
	v_cndmask_b32_e32 v114, v48, v52, vcc
	v_cndmask_b32_e32 v121, v23, v43, vcc
	v_cndmask_b32_e32 v124, v20, v40, vcc
	v_cndmask_b32_e32 v131, v15, v39, vcc
	v_cndmask_b32_e32 v129, v14, v38, vcc
	v_cndmask_b32_e32 v127, v13, v37, vcc
	v_cndmask_b32_e32 v126, v12, v36, vcc
	v_cndmask_b32_e32 v141, v11, v31, vcc
	v_cndmask_b32_e32 v139, v10, v30, vcc
	v_cndmask_b32_e32 v137, v9, v29, vcc
	v_cndmask_b32_e32 v135, v8, v28, vcc
	v_cndmask_b32_e32 v151, v7, v27, vcc
	v_cndmask_b32_e32 v149, v6, v26, vcc
	v_cndmask_b32_e32 v147, v5, v25, vcc
	v_cndmask_b32_e32 v145, v4, v24, vcc
	v_cndmask_b32_e32 v161, v3, v19, vcc
	v_cndmask_b32_e32 v159, v2, v18, vcc
	v_cndmask_b32_e32 v157, v1, v17, vcc
	v_cndmask_b32_e32 v155, v0, v16, vcc
	v_lshlrev_b32_e32 v0, 16, v56
	v_and_b32_e32 v1, 0xffff0000, v56
	v_lshlrev_b32_e32 v2, 16, v57
	v_and_b32_e32 v3, 0xffff0000, v57
	v_lshlrev_b32_e32 v4, 16, v58
	v_and_b32_e32 v5, 0xffff0000, v58
	v_lshlrev_b32_e32 v6, 16, v59
	v_and_b32_e32 v7, 0xffff0000, v59
	v_mad_i64_i32 v[8:9], s[2:3], v60, s10, 0
	v_lshlrev_b32_e32 v12, 16, v63
	v_and_b32_e32 v13, 0xffff0000, v63
	v_lshlrev_b32_e32 v14, 16, v62
	v_and_b32_e32 v15, 0xffff0000, v62
	v_lshlrev_b32_e32 v16, 16, v61
	v_and_b32_e32 v17, 0xffff0000, v61
	v_mad_i64_i32 v[18:19], s[2:3], v78, s10, 0
	v_lshlrev_b32_e32 v20, 16, v86
	v_and_b32_e32 v21, 0xffff0000, v86
	v_lshlrev_b32_e32 v22, 16, v85
	v_and_b32_e32 v23, 0xffff0000, v85
	v_lshlrev_b32_e32 v24, 16, v84
	v_and_b32_e32 v25, 0xffff0000, v84
	v_lshlrev_b32_e32 v26, 16, v79
	v_and_b32_e32 v27, 0xffff0000, v79
	v_mad_i64_i32 v[28:29], s[2:3], v87, s10, 0
	v_lshlrev_b32_e32 v30, 16, v91
	v_and_b32_e32 v31, 0xffff0000, v91
	v_lshlrev_b32_e32 v32, 16, v90
	v_and_b32_e32 v33, 0xffff0000, v90
	v_lshlrev_b32_e32 v34, 16, v89
	v_and_b32_e32 v35, 0xffff0000, v89
	v_lshlrev_b32_e32 v36, 16, v88
	v_and_b32_e32 v37, 0xffff0000, v88
	v_mad_i64_i32 v[38:39], s[2:3], v92, s10, 0
	v_lshlrev_b32_e32 v40, 16, v96
	v_and_b32_e32 v41, 0xffff0000, v96
	v_lshlrev_b32_e32 v46, 16, v93
	v_and_b32_e32 v47, 0xffff0000, v93
	v_mad_i64_i32 v[48:49], s[2:3], v97, s10, 0
	v_lshlrev_b32_e32 v50, 16, v101
	v_and_b32_e32 v51, 0xffff0000, v101
	v_lshlrev_b32_e32 v52, 16, v100
	v_and_b32_e32 v53, 0xffff0000, v100
	v_lshlrev_b32_e32 v54, 16, v99
	v_and_b32_e32 v55, 0xffff0000, v99
	v_lshlrev_b32_e32 v56, 16, v98
	v_and_b32_e32 v57, 0xffff0000, v98
	v_mad_i64_i32 v[58:59], s[2:3], v102, s10, 0
	v_lshlrev_b32_e32 v60, 16, v106
	v_and_b32_e32 v61, 0xffff0000, v106
	v_lshlrev_b32_e32 v62, 16, v105
	v_and_b32_e32 v63, 0xffff0000, v105
	v_lshlrev_b32_e32 v78, 16, v104
	v_and_b32_e32 v79, 0xffff0000, v104
	v_lshlrev_b32_e32 v84, 16, v103
	v_and_b32_e32 v85, 0xffff0000, v103
	v_lshlrev_b32_e32 v86, 16, v110
	v_and_b32_e32 v87, 0xffff0000, v110
	v_lshlrev_b32_e32 v88, 16, v109
	v_and_b32_e32 v89, 0xffff0000, v109
	v_lshlrev_b32_e32 v90, 16, v108
	v_and_b32_e32 v91, 0xffff0000, v108
	v_lshlrev_b32_e32 v92, 16, v107
	v_and_b32_e32 v93, 0xffff0000, v107
	v_lshlrev_b32_e32 v96, 16, v113
	v_and_b32_e32 v97, 0xffff0000, v113
	v_lshlrev_b32_e32 v98, 16, v112
	v_and_b32_e32 v99, 0xffff0000, v112
	v_lshlrev_b32_e32 v100, 16, v111
	v_and_b32_e32 v101, 0xffff0000, v111
	v_mad_i64_i32 v[102:103], s[2:3], v115, s10, 0
	v_lshlrev_b32_e32 v104, 16, v119
	v_and_b32_e32 v105, 0xffff0000, v119
	v_lshlrev_b32_e32 v106, 16, v118
	v_and_b32_e32 v107, 0xffff0000, v118
	v_lshlrev_b32_e32 v108, 16, v117
	v_and_b32_e32 v109, 0xffff0000, v117
	v_lshlrev_b32_e32 v110, 16, v116
	v_and_b32_e32 v111, 0xffff0000, v116
	v_mad_i64_i32 v[112:113], s[2:3], v120, s10, 0
	v_lshlrev_b32_e32 v116, 16, v123
; __device__ __forceinline__ unsigned pkbf(float lo, float hi) { typedef __bf16 bf2_t __attribute__((ext_vector_type(2))); f32x2 v = {lo, hi}; bf2_t b = __builtin_convertvector(v, bf2_t); return __builtin_bit_cast(unsigned, b); }
; __device__ __forceinline__ void phase_scan(const Args& a, unsigned char* ws, bf16* STB, int l, int vcu, int G, int tid, int z) {
;     ...
;         for (int i = 0; i < 16; ++i) {
;             const int n = dir ? 15 - i : i;
;             u32x4 w; w.x = pkbf(c[0], c[1]); w.y = pkbf(c[2], c[3]); w.z = pkbf(c[4], c[5]); w.w = pkbf(c[6], c[7]);
;             *(u32x4*)(base + (size_t)n * cst) = w;
; #pragma unroll
;             for (int e = 0; e < 4; ++e) { c[2 * e] = bflo(kv[n][e]) + g * c[2 * e]; c[2 * e + 1] = bfhi(kv[n][e]) + g * c[2 * e + 1]; }
;         }
	v_and_b32_e32 v117, 0xffff0000, v123
	v_lshlrev_b32_e32 v118, 16, v122
	v_and_b32_e32 v119, 0xffff0000, v122
	v_mad_i64_i32 v[122:123], s[2:3], v125, s10, 0
	v_mad_i64_i32 v[132:133], s[2:3], v132, s10, 0
	v_mad_i64_i32 v[142:143], s[2:3], v142, s10, 0
	v_mad_i64_i32 v[152:153], s[2:3], v152, s10, 0
	v_mad_i64_i32 v[162:163], s[2:3], v162, s10, 0
	v_lshl_add_u64 v[8:9], v[8:9], 1, v[72:73]
	v_lshl_add_u64 v[18:19], v[18:19], 1, v[72:73]
	v_lshl_add_u64 v[28:29], v[28:29], 1, v[72:73]
	v_lshl_add_u64 v[38:39], v[38:39], 1, v[72:73]
	v_lshl_add_u64 v[48:49], v[48:49], 1, v[72:73]
	v_lshl_add_u64 v[58:59], v[58:59], 1, v[72:73]
	v_lshl_add_u64 v[102:103], v[102:103], 1, v[72:73]
	v_lshl_add_u64 v[112:113], v[112:113], 1, v[72:73]
	v_lshl_add_u64 v[122:123], v[122:123], 1, v[72:73]
	v_lshl_add_u64 v[132:133], v[132:133], 1, v[72:73]
	v_lshl_add_u64 v[142:143], v[142:143], 1, v[72:73]
	v_lshl_add_u64 v[152:153], v[152:153], 1, v[72:73]
	v_lshl_add_u64 v[72:73], v[162:163], 1, v[72:73]
	v_mul_f32_e32 v162, 0, v64
	v_lshlrev_b32_e32 v10, 16, v67
	v_and_b32_e32 v11, 0xffff0000, v67
	v_pk_add_f32 v[164:165], v[162:163], v[0:1] op_sel_hi:[0,1]
	v_pk_add_f32 v[166:167], v[162:163], v[2:3] op_sel_hi:[0,1]
	v_pk_add_f32 v[4:5], v[162:163], v[4:5] op_sel_hi:[0,1]
	v_pk_add_f32 v[6:7], v[162:163], v[6:7] op_sel_hi:[0,1]
	v_cvt_pk_bf16_f32 v0, v164, v165
	v_cvt_pk_bf16_f32 v1, v166, v167
	v_cvt_pk_bf16_f32 v2, v4, v5
	v_cvt_pk_bf16_f32 v3, v6, v7
	v_pk_fma_f32 v[10:11], v[64:65], v[164:165], v[10:11] op_sel_hi:[0,1,1]
	v_pk_fma_f32 v[12:13], v[64:65], v[166:167], v[12:13] op_sel_hi:[0,1,1]
	v_pk_fma_f32 v[4:5], v[64:65], v[4:5], v[14:15] op_sel_hi:[0,1,1]
	v_pk_fma_f32 v[6:7], v[64:65], v[6:7], v[16:17] op_sel_hi:[0,1,1]
	global_store_dwordx4 v[8:9], v[0:3], off
	v_pk_fma_f32 v[8:9], v[64:65], v[10:11], v[20:21] op_sel_hi:[0,1,1]
	v_lshlrev_b32_e32 v42, 16, v95
	v_cvt_pk_bf16_f32 v0, v10, v11
	v_cvt_pk_bf16_f32 v1, v12, v13
	v_cvt_pk_bf16_f32 v2, v4, v5
	v_cvt_pk_bf16_f32 v3, v6, v7
	v_pk_fma_f32 v[10:11], v[64:65], v[12:13], v[22:23] op_sel_hi:[0,1,1]
	v_pk_fma_f32 v[4:5], v[64:65], v[4:5], v[24:25] op_sel_hi:[0,1,1]
	v_pk_fma_f32 v[6:7], v[64:65], v[6:7], v[26:27] op_sel_hi:[0,1,1]
	v_and_b32_e32 v43, 0xffff0000, v95
	v_lshlrev_b32_e32 v44, 16, v94
	v_and_b32_e32 v45, 0xffff0000, v94
	global_store_dwordx4 v[18:19], v[0:3], off
	v_lshlrev_b32_e32 v94, 16, v114
	v_and_b32_e32 v95, 0xffff0000, v114
	v_cvt_pk_bf16_f32 v0, v8, v9
	v_cvt_pk_bf16_f32 v1, v10, v11
	v_cvt_pk_bf16_f32 v2, v4, v5
	v_cvt_pk_bf16_f32 v3, v6, v7
	v_pk_fma_f32 v[8:9], v[64:65], v[8:9], v[30:31] op_sel_hi:[0,1,1]
	v_pk_fma_f32 v[10:11], v[64:65], v[10:11], v[32:33] op_sel_hi:[0,1,1]
	v_pk_fma_f32 v[4:5], v[64:65], v[4:5], v[34:35] op_sel_hi:[0,1,1]
	v_pk_fma_f32 v[6:7], v[64:65], v[6:7], v[36:37] op_sel_hi:[0,1,1]
	global_store_dwordx4 v[28:29], v[0:3], off
	v_lshlrev_b32_e32 v114, 16, v124
	v_and_b32_e32 v115, 0xffff0000, v124
	v_cvt_pk_bf16_f32 v0, v8, v9
	v_cvt_pk_bf16_f32 v1, v10, v11
	v_cvt_pk_bf16_f32 v2, v4, v5
	v_cvt_pk_bf16_f32 v3, v6, v7
	v_pk_fma_f32 v[8:9], v[64:65], v[8:9], v[40:41] op_sel_hi:[0,1,1]
	v_pk_fma_f32 v[10:11], v[64:65], v[10:11], v[42:43] op_sel_hi:[0,1,1]
	v_pk_fma_f32 v[4:5], v[64:65], v[4:5], v[44:45] op_sel_hi:[0,1,1]
	v_pk_fma_f32 v[6:7], v[64:65], v[6:7], v[46:47] op_sel_hi:[0,1,1]
	global_store_dwordx4 v[38:39], v[0:3], off
	v_lshlrev_b32_e32 v120, 16, v121
	v_and_b32_e32 v121, 0xffff0000, v121
	v_cvt_pk_bf16_f32 v0, v8, v9
	v_cvt_pk_bf16_f32 v1, v10, v11
	v_cvt_pk_bf16_f32 v2, v4, v5
	v_cvt_pk_bf16_f32 v3, v6, v7
	v_pk_fma_f32 v[8:9], v[64:65], v[8:9], v[50:51] op_sel_hi:[0,1,1]
	v_pk_fma_f32 v[10:11], v[64:65], v[10:11], v[52:53] op_sel_hi:[0,1,1]
	v_pk_fma_f32 v[4:5], v[64:65], v[4:5], v[54:55] op_sel_hi:[0,1,1]
	v_pk_fma_f32 v[6:7], v[64:65], v[6:7], v[56:57] op_sel_hi:[0,1,1]
	global_store_dwordx4 v[48:49], v[0:3], off
	v_lshlrev_b32_e32 v124, 16, v126
	v_and_b32_e32 v125, 0xffff0000, v126
	v_cvt_pk_bf16_f32 v0, v8, v9
	v_cvt_pk_bf16_f32 v1, v10, v11
	v_cvt_pk_bf16_f32 v2, v4, v5
	v_cvt_pk_bf16_f32 v3, v6, v7
	v_pk_fma_f32 v[8:9], v[64:65], v[8:9], v[60:61] op_sel_hi:[0,1,1]
	v_pk_fma_f32 v[10:11], v[64:65], v[10:11], v[62:63] op_sel_hi:[0,1,1]
	v_pk_fma_f32 v[4:5], v[64:65], v[4:5], v[78:79] op_sel_hi:[0,1,1]
	v_pk_fma_f32 v[6:7], v[64:65], v[6:7], v[84:85] op_sel_hi:[0,1,1]
	global_store_dwordx4 v[58:59], v[0:3], off
	v_lshlrev_b32_e32 v126, 16, v127
	v_and_b32_e32 v127, 0xffff0000, v127
	v_cvt_pk_bf16_f32 v0, v8, v9
	v_cvt_pk_bf16_f32 v1, v10, v11
	v_cvt_pk_bf16_f32 v2, v4, v5
	v_cvt_pk_bf16_f32 v3, v6, v7
	v_pk_fma_f32 v[8:9], v[64:65], v[8:9], v[86:87] op_sel_hi:[0,1,1]
; __device__ __forceinline__ unsigned pkbf(float lo, float hi) { typedef __bf16 bf2_t __attribute__((ext_vector_type(2))); f32x2 v = {lo, hi}; bf2_t b = __builtin_convertvector(v, bf2_t); return __builtin_bit_cast(unsigned, b); }
; __device__ __forceinline__ void phase_scan(const Args& a, unsigned char* ws, bf16* STB, int l, int vcu, int G, int tid, int z) {
;     ...
;         for (int i = 0; i < 16; ++i) {
;             const int n = dir ? 15 - i : i;
;             u32x4 w; w.x = pkbf(c[0], c[1]); w.y = pkbf(c[2], c[3]); w.z = pkbf(c[4], c[5]); w.w = pkbf(c[6], c[7]);
;             *(u32x4*)(base + (size_t)n * cst) = w;
; #pragma unroll
;             for (int e = 0; e < 4; ++e) { c[2 * e] = bflo(kv[n][e]) + g * c[2 * e]; c[2 * e + 1] = bfhi(kv[n][e]) + g * c[2 * e + 1]; }
;         }
	v_pk_fma_f32 v[10:11], v[64:65], v[10:11], v[88:89] op_sel_hi:[0,1,1]
	v_pk_fma_f32 v[4:5], v[64:65], v[4:5], v[90:91] op_sel_hi:[0,1,1]
	v_pk_fma_f32 v[6:7], v[64:65], v[6:7], v[92:93] op_sel_hi:[0,1,1]
	global_store_dwordx4 v[70:71], v[0:3], off
	v_lshlrev_b32_e32 v128, 16, v129
	v_and_b32_e32 v129, 0xffff0000, v129
	v_cvt_pk_bf16_f32 v0, v8, v9
	v_cvt_pk_bf16_f32 v1, v10, v11
	v_cvt_pk_bf16_f32 v2, v4, v5
	v_cvt_pk_bf16_f32 v3, v6, v7
	v_pk_fma_f32 v[8:9], v[64:65], v[8:9], v[94:95] op_sel_hi:[0,1,1]
	v_pk_fma_f32 v[10:11], v[64:65], v[10:11], v[96:97] op_sel_hi:[0,1,1]
	v_pk_fma_f32 v[4:5], v[64:65], v[4:5], v[98:99] op_sel_hi:[0,1,1]
	v_pk_fma_f32 v[6:7], v[64:65], v[6:7], v[100:101] op_sel_hi:[0,1,1]
	global_store_dwordx4 v[68:69], v[0:3], off
	v_lshlrev_b32_e32 v130, 16, v131
	v_and_b32_e32 v131, 0xffff0000, v131
	v_cvt_pk_bf16_f32 v0, v8, v9
	v_cvt_pk_bf16_f32 v1, v10, v11
	v_cvt_pk_bf16_f32 v2, v4, v5
	v_cvt_pk_bf16_f32 v3, v6, v7
	v_pk_fma_f32 v[8:9], v[64:65], v[8:9], v[104:105] op_sel_hi:[0,1,1]
	v_pk_fma_f32 v[10:11], v[64:65], v[10:11], v[106:107] op_sel_hi:[0,1,1]
	v_pk_fma_f32 v[4:5], v[64:65], v[4:5], v[108:109] op_sel_hi:[0,1,1]
	v_pk_fma_f32 v[6:7], v[64:65], v[6:7], v[110:111] op_sel_hi:[0,1,1]
	global_store_dwordx4 v[102:103], v[0:3], off
	v_lshlrev_b32_e32 v134, 16, v135
	v_and_b32_e32 v135, 0xffff0000, v135
	v_cvt_pk_bf16_f32 v0, v8, v9
	v_cvt_pk_bf16_f32 v1, v10, v11
	v_cvt_pk_bf16_f32 v2, v4, v5
	v_cvt_pk_bf16_f32 v3, v6, v7
	v_pk_fma_f32 v[8:9], v[64:65], v[8:9], v[114:115] op_sel_hi:[0,1,1]
	v_pk_fma_f32 v[10:11], v[64:65], v[10:11], v[116:117] op_sel_hi:[0,1,1]
	v_pk_fma_f32 v[4:5], v[64:65], v[4:5], v[118:119] op_sel_hi:[0,1,1]
	v_pk_fma_f32 v[6:7], v[64:65], v[6:7], v[120:121] op_sel_hi:[0,1,1]
	v_lshlrev_b32_e32 v136, 16, v137
	v_and_b32_e32 v137, 0xffff0000, v137
	v_lshlrev_b32_e32 v138, 16, v139
	v_and_b32_e32 v139, 0xffff0000, v139
	v_lshlrev_b32_e32 v140, 16, v141
	v_and_b32_e32 v141, 0xffff0000, v141
	global_store_dwordx4 v[112:113], v[0:3], off
	v_lshlrev_b32_e32 v144, 16, v145
	v_and_b32_e32 v145, 0xffff0000, v145
	v_cvt_pk_bf16_f32 v0, v8, v9
	v_cvt_pk_bf16_f32 v1, v10, v11
	v_cvt_pk_bf16_f32 v2, v4, v5
	v_cvt_pk_bf16_f32 v3, v6, v7
	v_pk_fma_f32 v[8:9], v[64:65], v[8:9], v[124:125] op_sel_hi:[0,1,1]
	v_pk_fma_f32 v[10:11], v[64:65], v[10:11], v[126:127] op_sel_hi:[0,1,1]
	v_pk_fma_f32 v[4:5], v[64:65], v[4:5], v[128:129] op_sel_hi:[0,1,1]
	v_pk_fma_f32 v[6:7], v[64:65], v[6:7], v[130:131] op_sel_hi:[0,1,1]
	v_lshlrev_b32_e32 v146, 16, v147
	v_and_b32_e32 v147, 0xffff0000, v147
	v_lshlrev_b32_e32 v148, 16, v149
	v_and_b32_e32 v149, 0xffff0000, v149
	v_lshlrev_b32_e32 v150, 16, v151
	v_and_b32_e32 v151, 0xffff0000, v151
	global_store_dwordx4 v[122:123], v[0:3], off
	v_lshlrev_b32_e32 v154, 16, v155
	v_and_b32_e32 v155, 0xffff0000, v155
	v_cvt_pk_bf16_f32 v0, v8, v9
	v_cvt_pk_bf16_f32 v1, v10, v11
	v_cvt_pk_bf16_f32 v2, v4, v5
	v_cvt_pk_bf16_f32 v3, v6, v7
	v_pk_fma_f32 v[8:9], v[64:65], v[8:9], v[134:135] op_sel_hi:[0,1,1]
	v_pk_fma_f32 v[10:11], v[64:65], v[10:11], v[136:137] op_sel_hi:[0,1,1]
	v_pk_fma_f32 v[4:5], v[64:65], v[4:5], v[138:139] op_sel_hi:[0,1,1]
	v_pk_fma_f32 v[6:7], v[64:65], v[6:7], v[140:141] op_sel_hi:[0,1,1]
	v_lshlrev_b32_e32 v156, 16, v157
	v_and_b32_e32 v157, 0xffff0000, v157
	v_lshlrev_b32_e32 v158, 16, v159
	v_and_b32_e32 v159, 0xffff0000, v159
	v_lshlrev_b32_e32 v160, 16, v161
	v_and_b32_e32 v161, 0xffff0000, v161
	global_store_dwordx4 v[132:133], v[0:3], off
	s_nop 1
	v_cvt_pk_bf16_f32 v0, v8, v9
	v_cvt_pk_bf16_f32 v1, v10, v11
	v_cvt_pk_bf16_f32 v2, v4, v5
	v_cvt_pk_bf16_f32 v3, v6, v7
	v_pk_fma_f32 v[8:9], v[64:65], v[8:9], v[144:145] op_sel_hi:[0,1,1]
	v_pk_fma_f32 v[10:11], v[64:65], v[10:11], v[146:147] op_sel_hi:[0,1,1]
	v_pk_fma_f32 v[4:5], v[64:65], v[4:5], v[148:149] op_sel_hi:[0,1,1]
	v_pk_fma_f32 v[6:7], v[64:65], v[6:7], v[150:151] op_sel_hi:[0,1,1]
	global_store_dwordx4 v[142:143], v[0:3], off
	s_nop 1
	v_cvt_pk_bf16_f32 v0, v8, v9
	v_cvt_pk_bf16_f32 v1, v10, v11
	v_cvt_pk_bf16_f32 v2, v4, v5
	v_cvt_pk_bf16_f32 v3, v6, v7
	v_pk_fma_f32 v[8:9], v[64:65], v[8:9], v[154:155] op_sel_hi:[0,1,1]
	v_pk_fma_f32 v[10:11], v[64:65], v[10:11], v[156:157] op_sel_hi:[0,1,1]
	v_pk_fma_f32 v[4:5], v[64:65], v[4:5], v[158:159] op_sel_hi:[0,1,1]
	v_pk_fma_f32 v[6:7], v[64:65], v[6:7], v[160:161] op_sel_hi:[0,1,1]
	global_store_dwordx4 v[152:153], v[0:3], off
	s_nop 1
	v_cvt_pk_bf16_f32 v0, v8, v9
	v_cvt_pk_bf16_f32 v1, v10, v11
	v_cvt_pk_bf16_f32 v2, v4, v5
	v_cvt_pk_bf16_f32 v3, v6, v7
	global_store_dwordx4 v[72:73], v[0:3], off
	s_andn2_b64 exec, exec, s[14:15]
	s_cbranch_execnz .LBB0_564

; #define LAS __attribute__((address_space(3)))
; __device__ __forceinline__ void ret_gammas(const Args& a, int l, int h, float& lgf2, float& lgb2) {
;     const float xf = a.in[8][(l * 2 + 0) * 4 + h], xb = a.in[8][(l * 2 + 1) * 4 + h];
;     lgf2 = -log1pf(expf(-xf)) * LOG2E; lgb2 = -log1pf(expf(-xb)) * LOG2E;
; __device__ __forceinline__ void r2_unit(const Args& a, unsigned char* ws, bf16* STB, LAS unsigned char* lds, int l, int unit, int tid, int wid, int lane, int dry) {
;     ...
;     const int n = unit & 15, h = (unit >> 4) & 3, b = unit >> 6;
;     float lgf2, lgb2; ret_gammas(a, l, h, lgf2, lgb2);
;     bf16* P = (bf16*)(ws + WS_P);
;     const bf16* kp = P + (size_t)(b * SEQ + n * 128) * NIN + 512 + h * 128;
;     const bf16* sp = STB + ((size_t)((b * 4 + h) * 16 + n) * 2) * 16384;
;     LAS unsigned char* KT = lds, * VT = lds + 32768, * SF = lds + 65536, * SB = lds + 98304;
; #pragma unroll
;     for (int i = 0; i < 4; ++i) {
;         const int c = tid + 512 * i, row = c >> 4, ch = c & 15; const unsigned o = offb(row, ch);
;         const u32x4 kv = *(const u32x4*)(kp + (size_t)row * NIN + ch * 8), vv = *(const u32x4*)(kp + 512 + (size_t)row * NIN + ch * 8);
;         const u32x4 sf = *(const u32x4*)(sp + row * 128 + ch * 8), sb = *(const u32x4*)(sp + 16384 + row * 128 + ch * 8);
.LBB0_664:
	s_bfe_u32 s44, s69, 0x20004
	s_lshl_b32 s2, s44, 2
	v_mov_b32_e32 v52, v176
	v_mov_b32_e32 v131, v199
	v_mov_b32_e32 v0, s2
	s_waitcnt lgkmcnt(0)
	s_load_dword s100, s[40:41], s2 offset:0x0
	s_load_dword s101, s[40:41], s2 offset:0x10
	s_and_b32 s3, s69, 15
	s_ashr_i32 s2, s69, 6
	s_lshl_b32 s6, s2, 11
	s_lshl_b32 s10, s3, 7
	s_or_b32 s6, s6, s10
	s_mul_hi_i32 s7, s6, 0x1c00
	s_mulk_i32 s6, 0x1c00
	s_add_u32 s6, s50, s6
	s_addc_u32 s7, s51, s7
	s_lshl_b32 s52, s44, 8
	s_add_u32 s6, s6, s52
	v_and_b32_e32 v68, 15, v52
	s_addc_u32 s7, s7, 0
	s_and_b32 s8, s69, 0xffffffc0
	s_lshl_b32 s9, s44, 4
	v_lshlrev_b32_e32 v124, 4, v68
	s_or_b32 s8, s9, s8
	v_lshl_add_u64 v[8:9], s[6:7], 0, v[124:125]
	s_or_b32 s6, s8, s3
	s_ashr_i32 s7, s6, 31
	s_lshl_b64 s[6:7], s[6:7], 16
	v_readlane_b32 s3, v238, 11
	s_add_u32 s6, s3, s6
	s_mov_b32 s3, 0xbfb8aa3b
	s_addc_u32 s7, s45, s7
	v_ashrrev_i32_e32 v69, 4, v52
	v_mad_i64_i32 v[4:5], s[8:9], v69, s61, v[8:9]
	s_mov_b32 s8, 0x3f2aaaab
	s_mov_b64 s[4:5], 0x8000
	global_load_dwordx4 v[0:3], v[4:5], off offset:1024
	s_nop 0
	global_load_dwordx4 v[4:7], v[4:5], off offset:2048
	v_add_u32_e32 v36, 0x400, v52
	v_ashrrev_i32_e32 v73, 4, v36
	v_lshlrev_b32_e32 v44, 7, v73
	v_ashrrev_i32_e32 v45, 31, v44
	v_lshlrev_b64 v[48:49], 1, v[44:45]
	v_ashrrev_i32_e32 v94, 5, v131
	v_lshlrev_b32_e32 v128, 3, v94
	v_ashrrev_i32_e32 v129, 31, v128
	v_lshlrev_b32_e32 v130, 2, v94
	s_waitcnt lgkmcnt(0)
	v_mov_b32_e32 v12, s100
	v_mov_b32_e32 v70, s101
	v_mul_f32_e32 v10, 0xbfb8aa3b, v12
	v_fma_f32 v11, v12, s3, -v10
	v_rndne_f32_e32 v13, v10
	v_fmac_f32_e32 v11, 0xb2a5705f, v12
	v_sub_f32_e32 v10, v10, v13
	v_add_f32_e32 v10, v10, v11
	v_cvt_i32_f32_e32 v13, v13
	v_exp_f32_e32 v14, v10
	v_lshl_add_u64 v[10:11], s[6:7], 0, v[124:125]
	s_mov_b32 s6, 0x42ce8ed0
	v_cmp_nlt_f32_e32 vcc, s6, v12
	v_ldexp_f32 v13, v14, v13
	s_mov_b32 s7, 0xc2b17218
	v_cndmask_b32_e32 v13, 0, v13, vcc
	v_cmp_ngt_f32_e32 vcc, s7, v12
	v_lshl_add_u64 v[60:61], v[10:11], 0, s[4:5]
	v_mad_i64_i32 v[40:41], s[4:5], v73, s61, v[8:9]
	v_cndmask_b32_e32 v71, v134, v13, vcc
	v_add_f32_e32 v14, 1.0, v71
	v_add_f32_e32 v15, -1.0, v14
	v_frexp_mant_f32_e32 v16, v14
	v_cvt_f64_f32_e32 v[12:13], v14
	v_sub_f32_e32 v17, v15, v14
	v_frexp_exp_i32_f64_e32 v12, v[12:13]
	v_cmp_gt_f32_e32 vcc, s8, v16
	v_sub_f32_e32 v15, v71, v15
	v_add_f32_e32 v13, 1.0, v17
	v_subbrev_co_u32_e32 v12, vcc, 0, v12, vcc
	v_add_f32_e32 v13, v15, v13
	v_sub_u32_e32 v15, 0, v12
	v_cvt_f32_i32_e32 v12, v12
	v_ldexp_f32 v14, v14, v15
	v_ldexp_f32 v13, v13, v15
	v_add_f32_e32 v15, -1.0, v14
	v_add_f32_e32 v16, 1.0, v14
	v_add_f32_e32 v17, 1.0, v15
	v_add_f32_e32 v18, -1.0, v16
	v_sub_f32_e32 v17, v14, v17
	v_sub_f32_e32 v14, v14, v18
	v_mul_f32_e32 v18, 0x3f317218, v12
	v_add_f32_e32 v17, v13, v17
	v_add_f32_e32 v13, v13, v14
	v_fma_f32 v14, v12, s96, -v18
	v_add_f32_e32 v19, v15, v17
	v_add_f32_e32 v20, v16, v13
	v_fmac_f32_e32 v14, 0xb102e308, v12
	v_sub_f32_e32 v12, v15, v19
	v_sub_f32_e32 v15, v16, v20
	v_rcp_f32_e32 v16, v20
	v_add_f32_e32 v21, v18, v14
	v_add_f32_e32 v13, v13, v15
	v_sub_f32_e32 v15, v21, v18
	v_sub_f32_e32 v14, v14, v15
	v_mul_f32_e32 v15, v19, v16
	v_add_f32_e32 v12, v17, v12
	v_mul_f32_e32 v17, v20, v15
	v_fma_f32 v18, v15, v20, -v17
	v_fmac_f32_e32 v18, v15, v13
	v_add_f32_e32 v22, v17, v18
	v_sub_f32_e32 v23, v19, v22
	v_sub_f32_e32 v17, v22, v17
	v_sub_f32_e32 v19, v19, v23
	v_sub_f32_e32 v17, v17, v18
	v_sub_f32_e32 v18, v19, v22
	v_add_f32_e32 v12, v12, v18
	v_add_f32_e32 v12, v17, v12
	v_add_f32_e32 v17, v23, v12
	v_mul_f32_e32 v18, v16, v17
	v_sub_f32_e32 v19, v23, v17
	v_mul_f32_e32 v22, v20, v18
	v_add_f32_e32 v12, v12, v19
	v_add_f32_e32 v19, v15, v18
	v_fma_f32 v20, v18, v20, -v22
	v_sub_f32_e32 v15, v19, v15
	v_fmac_f32_e32 v20, v18, v13
	v_sub_f32_e32 v13, v18, v15
	v_add_f32_e32 v15, v22, v20
	v_sub_f32_e32 v18, v15, v22
	v_sub_f32_e32 v22, v17, v15
	v_sub_f32_e32 v17, v17, v22
	v_sub_f32_e32 v15, v17, v15
	v_sub_f32_e32 v18, v18, v20
	v_add_f32_e32 v12, v12, v15
	v_add_f32_e32 v12, v18, v12
	v_add_f32_e32 v12, v22, v12
	v_mul_f32_e32 v12, v16, v12
	v_add_f32_e32 v12, v13, v12
	v_add_f32_e32 v13, v19, v12
	v_mul_f32_e32 v15, v13, v13
	v_fmamk_f32 v18, v15, 0x3e9b6dac, v135
	v_sub_f32_e32 v16, v13, v19
	v_ldexp_f32 v17, v13, 1
	v_mul_f32_e32 v13, v13, v15
	v_fmaak_f32 v15, v15, v18, 0x3f2aaada
	v_mul_f32_e32 v13, v13, v15
	v_add_f32_e32 v15, v17, v13
	v_sub_f32_e32 v12, v12, v16
	v_sub_f32_e32 v16, v15, v17
	v_ldexp_f32 v12, v12, 1
	v_sub_f32_e32 v13, v13, v16
	v_add_f32_e32 v12, v12, v13
	v_add_f32_e32 v13, v15, v12
	v_sub_f32_e32 v15, v13, v15
	v_add_f32_e32 v53, v21, v13
	v_sub_f32_e32 v12, v12, v15
	v_sub_f32_e32 v15, v53, v21
	v_sub_f32_e32 v16, v53, v15
	v_add_f32_e32 v54, v14, v12
	v_sub_f32_e32 v13, v13, v15
	v_sub_f32_e32 v15, v21, v16
	v_sub_f32_e32 v16, v54, v14
	v_add_f32_e32 v55, v13, v15
	v_sub_f32_e32 v13, v54, v16
	v_sub_f32_e32 v12, v12, v16
	v_sub_f32_e32 v13, v14, v13
	v_add_f32_e32 v62, v12, v13
	v_lshlrev_b32_e32 v12, 7, v69
	v_ashrrev_i32_e32 v13, 31, v12
	v_lshlrev_b64 v[16:17], 1, v[12:13]
	v_lshl_add_u64 v[12:13], v[10:11], 0, v[16:17]
	v_add_u32_e32 v20, 0x200, v52
	global_load_dwordx4 v[12:15], v[12:13], off
	v_lshl_add_u64 v[16:17], v[60:61], 0, v[16:17]
	v_ashrrev_i32_e32 v72, 4, v20
	global_load_dwordx4 v[16:19], v[16:17], off
	v_lshlrev_b32_e32 v28, 7, v72
	v_ashrrev_i32_e32 v29, 31, v28
	v_mad_i64_i32 v[24:25], s[4:5], v72, s61, v[8:9]
	v_lshlrev_b64 v[32:33], 1, v[28:29]
	global_load_dwordx4 v[20:23], v[24:25], off offset:1024
	s_nop 0
	global_load_dwordx4 v[24:27], v[24:25], off offset:2048
	v_lshl_add_u64 v[28:29], v[10:11], 0, v[32:33]
	global_load_dwordx4 v[28:31], v[28:29], off
	v_lshl_add_u64 v[32:33], v[60:61], 0, v[32:33]
	global_load_dwordx4 v[32:35], v[32:33], off
	s_nop 0
	global_load_dwordx4 v[36:39], v[40:41], off offset:1024
	s_nop 0
	global_load_dwordx4 v[40:43], v[40:41], off offset:2048
	v_lshl_add_u64 v[44:45], v[10:11], 0, v[48:49]
	global_load_dwordx4 v[44:47], v[44:45], off
	v_lshl_add_u64 v[48:49], v[60:61], 0, v[48:49]
	global_load_dwordx4 v[48:51], v[48:49], off
	v_add_u32_e32 v52, 0x600, v52
	v_add_f32_e32 v63, v54, v55
	v_ashrrev_i32_e32 v74, 4, v52
	v_add_f32_e32 v64, v53, v63
	v_mad_i64_i32 v[8:9], s[4:5], v74, s61, v[8:9]
	v_sub_f32_e32 v65, v64, v53
	global_load_dwordx4 v[52:55], v[8:9], off offset:1024
	global_load_dwordx4 v[56:59], v[8:9], off offset:2048
	v_sub_f32_e32 v8, v63, v65
	v_add_f32_e32 v8, v62, v8
	v_add_f32_e32 v75, v64, v8
	s_waitcnt vmcnt(14)
; #define LAS __attribute__((address_space(3)))
; __device__ __forceinline__ int crow(int r, int hi) { return (r & 3) + 8 * (r >> 2) + 4 * hi; }
; __device__ __forceinline__ void r2_unit(const Args& a, unsigned char* ws, bf16* STB, LAS unsigned char* lds, int l, int unit, int tid, int wid, int lane, int dry) {
;     ...
; #pragma unroll
;     for (int i = 0; i < 4; ++i) {
;         const int c = tid + 512 * i, row = c >> 4, ch = c & 15; const unsigned o = offb(row, ch);
;         const u32x4 kv = *(const u32x4*)(kp + (size_t)row * NIN + ch * 8), vv = *(const u32x4*)(kp + 512 + (size_t)row * NIN + ch * 8);
;         const u32x4 sf = *(const u32x4*)(sp + row * 128 + ch * 8), sb = *(const u32x4*)(sp + 16384 + row * 128 + ch * 8);
;         *(LAS u32x4*)(KT + o) = kv; *(LAS u32x4*)(VT + o) = vv; *(LAS u32x4*)(SF + o) = sf; *(LAS u32x4*)(SB + o) = sb;
;     }
;     const int r32 = lane & 31, hi = lane >> 5, g1 = (lane >> 4) & 1, q4 = (lane & 15) >> 2, p4 = lane & 3;
;     const int cb = wid & 3, eh = wid >> 2;
;     const int cl = 32 * cb + r32;
;     const size_t tok = (size_t)b * SEQ + n * 128 + cl;
;     bf16x8 qf[8];
; #pragma unroll
;     for (int kd = 0; kd < 8; ++kd) qf[kd] = *(const bf16x8*)(P + tok * NIN + h * 128 + 16 * kd + 8 * hi);
;     __syncthreads();
;     f32x16 O[2], XF[2], XB[2];
; #pragma unroll
;     for (int e = 0; e < 2; ++e)
; #pragma unroll
;         for (int r = 0; r < 16; ++r) { O[e][r] = 0.f; XF[e][r] = 0.f; XB[e][r] = 0.f; }
;     float ff[16], fb[16];
; #pragma unroll
;     for (int r = 0; r < 16; ++r) { ff[r] = __builtin_amdgcn_exp2f((float)(31 - crow(r, hi)) * lgf2); fb[r] = __builtin_amdgcn_exp2f((float)crow(r, hi) * lgb2); }
	v_mul_f32_e32 v8, 0xbfb8aa3b, v70
	v_fma_f32 v9, v70, s3, -v8
	v_rndne_f32_e32 v62, v8
	v_fmac_f32_e32 v9, 0xb2a5705f, v70
	v_sub_f32_e32 v8, v8, v62
	v_add_f32_e32 v8, v8, v9
	v_exp_f32_e32 v76, v8
	v_lshlrev_b32_e32 v8, 7, v74
	v_ashrrev_i32_e32 v9, 31, v8
	v_lshlrev_b64 v[8:9], 1, v[8:9]
	v_lshl_add_u64 v[10:11], v[10:11], 0, v[8:9]
	v_cvt_i32_f32_e32 v77, v62
	v_lshl_add_u64 v[8:9], v[60:61], 0, v[8:9]
	global_load_dwordx4 v[60:63], v[10:11], off
	global_load_dwordx4 v[64:67], v[8:9], off
	s_mov_b32 s3, 0x7f800000
	v_cmp_neq_f32_e32 vcc, s3, v71
	v_ldexp_f32 v9, v76, v77
	s_nop 0
	v_cndmask_b32_e32 v8, v134, v75, vcc
	v_cmp_lt_f32_e64 vcc, |v71|, s60
	s_nop 1
	v_cndmask_b32_e32 v8, v8, v71, vcc
	v_cmp_nlt_f32_e32 vcc, s6, v70
	v_mul_f32_e32 v138, 0xbfb8aa3b, v8
	v_bfe_u32 v8, v131, 2, 2
	v_cndmask_b32_e32 v9, 0, v9, vcc
	v_cmp_ngt_f32_e32 vcc, s7, v70
	v_lshlrev_b32_e32 v70, 2, v69
	v_and_b32_e32 v70, 12, v70
	v_cndmask_b32_e32 v9, v134, v9, vcc
	v_add_f32_e32 v11, 1.0, v9
	v_frexp_mant_f32_e32 v10, v11
	v_cmp_gt_f32_e64 s[8:9], s8, v10
	v_lshlrev_b32_e32 v10, 8, v69
	v_bfe_u32 v69, v69, 2, 2
	v_bitop3_b32 v69, v70, v68, v69 bitop3:0x36
	v_lshl_or_b32 v10, v69, 4, v10
	v_add_u32_e32 v69, s70, v10
	s_waitcnt vmcnt(15)
	ds_write_b128 v69, v[0:3]
	s_waitcnt vmcnt(14)
	ds_write_b128 v69, v[4:7] offset:32768
	v_add_u32_e32 v0, s67, v10
	v_lshlrev_b32_e32 v1, 2, v72
	v_and_b32_e32 v1, 12, v1
	v_bfe_u32 v2, v72, 2, 2
	v_bitop3_b32 v1, v1, v68, v2 bitop3:0x36
	v_bfe_u32 v2, v73, 2, 2
	v_cmp_neq_f32_e64 s[4:5], s3, v9
	s_ashr_i32 s3, s2, 31
	s_lshl_b64 s[2:3], s[2:3], 11
	s_or_b32 s2, s2, s10
	s_waitcnt vmcnt(13)
	ds_write_b128 v0, v[12:15]
	v_add_u32_e32 v0, s46, v10
	v_and_b32_e32 v10, 31, v131
	s_waitcnt vmcnt(12)
	ds_write_b128 v0, v[16:19]
	v_lshlrev_b32_e32 v0, 8, v72
	v_lshl_or_b32 v0, v1, 4, v0
	v_add_u32_e32 v1, s70, v0
	s_waitcnt vmcnt(11)
	ds_write_b128 v1, v[20:23]
	s_waitcnt vmcnt(10)
	ds_write_b128 v1, v[24:27] offset:32768
	v_add_u32_e32 v1, s67, v0
	s_waitcnt vmcnt(9)
	ds_write_b128 v1, v[28:31]
	v_lshlrev_b32_e32 v1, 2, v73
	v_add_u32_e32 v0, s46, v0
	v_and_b32_e32 v1, 12, v1
	s_waitcnt vmcnt(8)
	ds_write_b128 v0, v[32:35]
	v_lshlrev_b32_e32 v0, 8, v73
	v_bitop3_b32 v1, v1, v68, v2 bitop3:0x36
	v_lshl_or_b32 v0, v1, 4, v0
	v_add_u32_e32 v1, s70, v0
	s_waitcnt vmcnt(7)
	ds_write_b128 v1, v[36:39]
	s_waitcnt vmcnt(6)
	ds_write_b128 v1, v[40:43] offset:32768
	v_add_u32_e32 v1, s67, v0
	s_waitcnt vmcnt(5)
	ds_write_b128 v1, v[44:47]
	v_lshlrev_b32_e32 v1, 2, v74
	v_add_u32_e32 v0, s46, v0
	v_and_b32_e32 v1, 12, v1
	v_bfe_u32 v2, v74, 2, 2
	s_waitcnt vmcnt(4)
	ds_write_b128 v0, v[48:51]
	v_lshlrev_b32_e32 v0, 8, v74
	v_bitop3_b32 v1, v1, v68, v2 bitop3:0x36
	v_lshl_or_b32 v2, v1, 4, v0
	v_add_u32_e32 v0, s70, v2
	v_or_b32_e32 v124, s33, v10
	s_waitcnt vmcnt(3)
	ds_write_b128 v0, v[52:55]
	s_waitcnt vmcnt(2)
	ds_write_b128 v0, v[56:59] offset:32768
	v_or_b32_e32 v0, s2, v124
	v_mad_u64_u32 v[0:1], s[10:11], v0, s61, v[126:127]
	v_mad_i32_i24 v1, s3, v136, v1
	v_lshl_add_u64 v[132:133], v[0:1], 0, s[52:53]
	v_lshl_add_u64 v[0:1], v[128:129], 1, v[132:133]
	global_load_dwordx4 v[48:51], v[0:1], off
	v_add_u32_e32 v3, s67, v2
	v_add_u32_e32 v2, s46, v2
	s_waitcnt vmcnt(2)
	ds_write_b128 v3, v[60:63]
	s_waitcnt vmcnt(1)
	ds_write_b128 v2, v[64:67]
	global_load_dwordx4 v[120:123], v[0:1], off offset:32
	global_load_dwordx4 v[116:119], v[0:1], off offset:64
	global_load_dwordx4 v[112:115], v[0:1], off offset:96
	global_load_dwordx4 v[108:111], v[0:1], off offset:128
	global_load_dwordx4 v[104:107], v[0:1], off offset:160
	global_load_dwordx4 v[100:103], v[0:1], off offset:192
	global_load_dwordx4 v[96:99], v[0:1], off offset:224
	v_sub_u32_e32 v0, 31, v130
	v_or_b32_e32 v40, 1, v130
	v_cvt_f32_i32_e32 v0, v0
	v_sub_u32_e32 v1, 31, v40
	v_cvt_f32_i32_e32 v1, v1
	v_or_b32_e32 v41, 2, v130
	v_mul_f32_e32 v0, v138, v0
	v_exp_f32_e32 v52, v0
	v_mul_f32_e32 v0, v138, v1
	v_sub_u32_e32 v1, 31, v41
	v_or_b32_e32 v69, 3, v130
	v_cvt_f32_i32_e32 v1, v1
	v_sub_u32_e32 v2, 31, v69
	v_cvt_f32_i32_e32 v2, v2
	v_exp_f32_e32 v53, v0
	v_mul_f32_e32 v0, v138, v1
	v_sub_u32_e32 v1, 23, v130
	v_exp_f32_e32 v54, v0
	v_mul_f32_e32 v0, v138, v2
	v_cvt_f32_i32_e32 v1, v1
	v_sub_u32_e32 v2, 22, v130
	v_cvt_f32_i32_e32 v2, v2
	v_exp_f32_e32 v55, v0
	v_mul_f32_e32 v0, v138, v1
	v_sub_u32_e32 v1, 21, v130
	v_exp_f32_e32 v56, v0
	v_mul_f32_e32 v0, v138, v2
	v_cvt_f32_i32_e32 v1, v1
	v_sub_u32_e32 v2, 20, v130
	v_cvt_f32_i32_e32 v2, v2
	v_exp_f32_e32 v57, v0
	v_mul_f32_e32 v0, v138, v1
	v_sub_u32_e32 v1, 15, v130
	v_exp_f32_e32 v58, v0
	v_mul_f32_e32 v0, v138, v2
	v_cvt_f32_i32_e32 v1, v1
	v_sub_u32_e32 v2, 14, v130
	v_cvt_f32_i32_e32 v2, v2
	v_exp_f32_e32 v59, v0
	v_mul_f32_e32 v0, v138, v1
	v_exp_f32_e32 v60, v0
	v_mul_f32_e32 v0, v138, v2
	v_exp_f32_e32 v61, v0
	v_sub_u32_e32 v0, 13, v130
	v_cvt_f32_i32_e32 v4, v0
	v_sub_u32_e32 v0, 12, v130
	v_cvt_f32_i32_e32 v5, v0
	v_lshlrev_b32_e32 v0, 2, v131
	v_and_b32_e32 v12, 12, v0
	v_lshlrev_b32_e32 v0, 8, v131
	v_and_b32_e32 v13, 0x1f00, v0
	v_bitop3_b32 v0, v12, v94, v8 bitop3:0x36
	v_lshl_add_u32 v0, v0, 4, v13
	v_add_u32_e32 v140, s70, v0
	s_waitcnt lgkmcnt(0)
	s_barrier
; #define LAS __attribute__((address_space(3)))
; __device__ __forceinline__ void r2_unit(const Args& a, unsigned char* ws, bf16* STB, LAS unsigned char* lds, int l, int unit, int tid, int wid, int lane, int dry) {
;     ...
;     for (int mb = 0; mb < 4; ++mb) {
;         f32x16 S;
; #pragma unroll
;         for (int r = 0; r < 16; ++r) S[r] = 0.f;
; #pragma unroll
;         for (int kd = 0; kd < 8; ++kd) { const bf16x8 kf = *(const LAS bf16x8*)(KT + kb[kd] + 8192 * mb); S = __builtin_amdgcn_mfma_f32_32x32x16_bf16(kf, qf[kd], S, 0, 0, 0); }
;         if (mb < cb) { const float fa = __builtin_amdgcn_exp2f((float)(cl - 32 * mb - 31) * lgf2);
; #pragma unroll
;             for (int r = 0; r < 16; ++r) S[r] *= fa * ff[r];
;         } else if (mb > cb) { const float fa = __builtin_amdgcn_exp2f((float)(32 * mb - cl) * lgb2);
; #pragma unroll
;             for (int r = 0; r < 16; ++r) S[r] *= fa * fb[r];
	ds_read_b128 v[0:3], v140
	v_mul_f32_e32 v4, v138, v4
	v_exp_f32_e32 v62, v4
	v_add_u32_e32 v4, 2, v94
	v_bitop3_b32 v4, v12, v4, v8 bitop3:0x36
	v_lshl_add_u32 v4, v4, 4, v13
	v_add_u32_e32 v141, s70, v4
	v_mul_f32_e32 v14, v138, v5
	ds_read_b128 v[4:7], v141
	s_waitcnt vmcnt(7) lgkmcnt(1)
	v_mfma_f32_32x32x16_bf16 v[18:33], v[0:3], v[48:51], 0
	v_sub_u32_e32 v0, 7, v130
	v_cvt_f32_i32_e32 v15, v0
	v_add_u32_e32 v0, 4, v94
	v_bitop3_b32 v0, v12, v0, v8 bitop3:0x36
	v_lshl_add_u32 v0, v0, 4, v13
	v_add_u32_e32 v143, s70, v0
	ds_read_b128 v[0:3], v143
	s_waitcnt vmcnt(6) lgkmcnt(1)
	v_mfma_f32_32x32x16_bf16 v[18:33], v[4:7], v[120:123], v[18:33]
	v_add_u32_e32 v4, 6, v94
	v_bitop3_b32 v4, v12, v4, v8 bitop3:0x36
	v_lshl_add_u32 v4, v4, 4, v13
	v_add_u32_e32 v144, s70, v4
	ds_read_b128 v[4:7], v144
	v_exp_f32_e32 v63, v14
	v_mul_f32_e32 v14, v138, v15
	s_waitcnt vmcnt(5) lgkmcnt(1)
	v_mfma_f32_32x32x16_bf16 v[18:33], v[0:3], v[116:119], v[18:33]
	v_sub_u32_e32 v0, 6, v130
	v_cvt_f32_i32_e32 v15, v0
	v_add_u32_e32 v0, 8, v94
	v_bitop3_b32 v0, v12, v0, v8 bitop3:0x36
	v_lshl_add_u32 v0, v0, 4, v13
	v_add_u32_e32 v146, s70, v0
	ds_read_b128 v[0:3], v146
	s_waitcnt vmcnt(4) lgkmcnt(1)
	v_mfma_f32_32x32x16_bf16 v[18:33], v[4:7], v[112:115], v[18:33]
	v_add_u32_e32 v4, 10, v94
	v_bitop3_b32 v4, v12, v4, v8 bitop3:0x36
	v_lshl_add_u32 v4, v4, 4, v13
	v_add_u32_e32 v148, s70, v4
	ds_read_b128 v[4:7], v148
	v_exp_f32_e32 v64, v14
	v_mul_f32_e32 v14, v138, v15
	s_waitcnt vmcnt(3) lgkmcnt(1)
	v_mfma_f32_32x32x16_bf16 v[18:33], v[0:3], v[108:111], v[18:33]
	v_sub_u32_e32 v0, 5, v130
	v_cvt_f32_i32_e32 v15, v0
	v_add_u32_e32 v0, 12, v94
	v_bitop3_b32 v0, v12, v0, v8 bitop3:0x36
	v_lshl_add_u32 v0, v0, 4, v13
	v_add_u32_e32 v150, s70, v0
	ds_read_b128 v[0:3], v150
	s_waitcnt vmcnt(2) lgkmcnt(1)
	v_mfma_f32_32x32x16_bf16 v[18:33], v[4:7], v[104:107], v[18:33]
	v_sub_u32_e32 v4, 4, v130
	v_cvt_f32_i32_e32 v16, v4
	v_add_u32_e32 v4, 14, v94
	v_bitop3_b32 v4, v12, v4, v8 bitop3:0x36
	v_lshl_add_u32 v4, v4, 4, v13
	v_add_u32_e32 v153, s70, v4
	ds_read_b128 v[4:7], v153
	s_waitcnt vmcnt(1) lgkmcnt(1)
	v_mfma_f32_32x32x16_bf16 v[18:33], v[0:3], v[100:103], v[18:33]
	v_mul_f32_e32 v0, v138, v15
	v_exp_f32_e32 v180, v0
	v_mul_f32_e32 v0, v138, v16
	v_exp_f32_e32 v65, v14
	v_exp_f32_e32 v181, v0
	v_cmp_lt_f32_e64 s[6:7], |v9|, s60
	v_cmp_ne_u32_e64 s[2:3], 1, v137
	s_waitcnt vmcnt(0) lgkmcnt(0)
	v_mfma_f32_32x32x16_bf16 v[18:33], v[4:7], v[96:99], v[18:33]
	s_andn2_b64 vcc, exec, s[54:55]
	s_cbranch_vccnz .LBB0_666
	v_subrev_u32_e32 v0, 31, v124
	v_cvt_f32_i32_e32 v0, v0
	s_mov_b64 s[10:11], 0
	v_mul_f32_e32 v0, v138, v0
	v_exp_f32_e32 v12, v0
	s_nop 0
	v_pk_mul_f32 v[2:3], v[12:13], v[54:55] op_sel_hi:[0,1]
	v_pk_mul_f32 v[6:7], v[12:13], v[56:57] op_sel_hi:[0,1]
	v_pk_mul_f32 v[14:15], v[12:13], v[58:59] op_sel_hi:[0,1]
	s_nop 0
	v_pk_mul_f32 v[4:5], v[20:21], v[2:3]
	v_pk_mul_f32 v[2:3], v[22:23], v[6:7]
	v_pk_mul_f32 v[6:7], v[24:25], v[14:15]
	v_pk_mul_f32 v[14:15], v[12:13], v[60:61] op_sel_hi:[0,1]
	v_pk_mul_f32 v[34:35], v[26:27], v[14:15]
	v_pk_mul_f32 v[14:15], v[12:13], v[62:63] op_sel_hi:[0,1]
	v_pk_mul_f32 v[0:1], v[12:13], v[52:53] op_sel_hi:[0,1]
	v_pk_mul_f32 v[36:37], v[28:29], v[14:15]
	v_pk_mul_f32 v[14:15], v[12:13], v[64:65] op_sel_hi:[0,1]
	v_mul_f32_e32 v13, v12, v180
	v_pk_mul_f32 v[0:1], v[18:19], v[0:1]
	v_pk_mul_f32 v[38:39], v[30:31], v[14:15]
	v_mul_f32_e32 v42, v32, v13
	v_mul_f32_e32 v43, v12, v181
	s_branch .LBB0_667

; __device__ __forceinline__ void ret_gammas(const Args& a, int l, int h, float& lgf2, float& lgb2) {
;     const float xf = a.in[8][(l * 2 + 0) * 4 + h], xb = a.in[8][(l * 2 + 1) * 4 + h];
;     lgf2 = -log1pf(expf(-xf)) * LOG2E; lgb2 = -log1pf(expf(-xb)) * LOG2E;
; __device__ __forceinline__ void phase_scan(const Args& a, unsigned char* ws, bf16* STB, int l, int vcu, int G, int tid, int z) {
;     ...
;     for (int it = gt; it < 192 * 2 * 2048; it += NT) {
;         const int grp = it & 2047, dir = (it >> 11) & 1, bh = it >> 12, h = bh & 3;
;         float lgf2, lgb2; ret_gammas(a, l, h, lgf2, lgb2);
;         const float g = __builtin_amdgcn_exp2f(128.f * (dir ? lgb2 : lgf2));
;         bf16* base = ST + ((size_t)(bh * 16) * 2 + dir) * 16384 + grp * 8;
;         u32x4 kv[16];
;         const size_t cst = (size_t)(32768 + z);
; #pragma unroll
;         for (int n = 0; n < 16; ++n) kv[n] = *(const u32x4*)(base + (size_t)n * cst);
.LBB0_1292:
	v_ashrrev_i32_e32 v1, 12, v74
	v_lshlrev_b32_e32 v3, 2, v1
	v_and_b32_e32 v3, 12, v3
	global_load_dword v67, v3, s[6:7] offset:32
	global_load_dword v79, v3, s[6:7] offset:48
	v_lshlrev_b32_e32 v4, 4, v1
	v_ashrrev_i32_e32 v5, 31, v4
	v_bfe_u32 v78, v74, 11, 1
	v_lshlrev_b64 v[4:5], 16, v[4:5]
	v_and_b32_e32 v2, 0x3ff8, v75
	v_lshlrev_b32_e32 v64, 15, v78
	v_lshl_add_u64 v[4:5], s[8:9], 0, v[4:5]
	v_lshl_add_u64 v[4:5], v[4:5], 0, v[64:65]
	v_lshlrev_b32_e32 v64, 1, v2
	v_lshl_add_u64 v[72:73], v[4:5], 0, v[64:65]
	v_lshl_add_u64 v[4:5], s[10:11], 1, v[72:73]
	v_lshl_add_u64 v[12:13], v[4:5], 0, s[12:13]
	v_bfe_i32 v0, v74, 11, 1
	v_lshl_add_u64 v[14:15], v[12:13], 0, s[12:13]
	v_and_b32_e32 v0, 15, v0
	v_add_u32_e32 v6, 7, v78
	v_sub_u32_e32 v8, 8, v78
	v_lshl_add_u64 v[16:17], v[14:15], 0, s[12:13]
	v_mad_i64_i32 v[0:1], s[2:3], v0, s10, 0
	v_mad_i64_i32 v[6:7], s[2:3], v6, s10, 0
	v_mad_i64_i32 v[8:9], s[2:3], v8, s10, 0
	v_lshl_add_u64 v[18:19], v[16:17], 0, s[12:13]
	v_lshl_add_u64 v[84:85], v[0:1], 1, v[72:73]
	v_lshl_add_u64 v[70:71], v[6:7], 1, v[72:73]
	v_lshl_add_u64 v[68:69], v[8:9], 1, v[72:73]
	global_load_dwordx4 v[56:59], v[72:73], off
	global_load_dwordx4 v[0:3], v[4:5], off
	s_nop 0
	global_load_dwordx4 v[4:7], v[12:13], off
	global_load_dwordx4 v[8:11], v[14:15], off
	s_nop 0
	global_load_dwordx4 v[12:15], v[16:17], off
	global_load_dwordx4 v[20:23], v[18:19], off
	v_lshl_add_u64 v[16:17], v[18:19], 0, s[12:13]
	global_load_dwordx4 v[32:35], v[16:17], off
	v_lshl_add_u64 v[16:17], v[16:17], 0, s[12:13]
	global_load_dwordx4 v[48:51], v[16:17], off
	v_lshl_add_u64 v[16:17], v[16:17], 0, s[12:13]
	global_load_dwordx4 v[52:55], v[16:17], off
	v_lshl_add_u64 v[16:17], v[16:17], 0, s[12:13]
	global_load_dwordx4 v[44:47], v[16:17], off
	v_lshl_add_u64 v[16:17], v[16:17], 0, s[12:13]
	global_load_dwordx4 v[40:43], v[16:17], off
	v_lshl_add_u64 v[16:17], v[16:17], 0, s[12:13]
	global_load_dwordx4 v[36:39], v[16:17], off
	v_lshl_add_u64 v[16:17], v[16:17], 0, s[12:13]
	global_load_dwordx4 v[28:31], v[16:17], off
	v_lshl_add_u64 v[16:17], v[16:17], 0, s[12:13]
	v_lshl_add_u64 v[60:61], v[16:17], 0, s[12:13]
	global_load_dwordx4 v[24:27], v[16:17], off
	v_add_u32_e32 v74, s0, v74
	global_load_dwordx4 v[16:19], v[60:61], off
	v_lshl_add_u64 v[60:61], v[60:61], 0, s[12:13]
	global_load_dwordx4 v[60:63], v[60:61], off
	v_cmp_lt_i32_e32 vcc, s23, v74
	global_store_dwordx4 v[84:85], v[80:83], off
	s_or_b64 s[14:15], vcc, s[14:15]
	v_add_u32_e32 v75, s1, v75
	s_waitcnt vmcnt(17)
	v_mul_f32_e32 v64, 0xbfb8aa3b, v67
	v_mul_f32_e32 v84, 0xbfb8aa3b, v79
	v_fma_f32 v85, v67, s16, -v64
	v_rndne_f32_e32 v86, v64
	v_fma_f32 v87, v79, s16, -v84
	v_rndne_f32_e32 v88, v84
	v_fmac_f32_e32 v85, 0xb2a5705f, v67
	v_sub_f32_e32 v64, v64, v86
	v_fmac_f32_e32 v87, 0xb2a5705f, v79
	v_sub_f32_e32 v84, v84, v88
	v_add_f32_e32 v64, v64, v85
	v_cvt_i32_f32_e32 v86, v86
	v_add_f32_e32 v84, v84, v87
	v_exp_f32_e32 v64, v64
	v_cvt_i32_f32_e32 v88, v88
	v_exp_f32_e32 v84, v84
	v_cmp_nlt_f32_e64 s[2:3], s17, v67
	v_ldexp_f32 v64, v64, v86
	v_cmp_nlt_f32_e32 vcc, s17, v79
	v_ldexp_f32 v84, v84, v88
	v_cndmask_b32_e64 v64, 0, v64, s[2:3]
	v_cmp_ngt_f32_e64 s[2:3], s18, v67
	v_cndmask_b32_e32 v84, 0, v84, vcc
	v_cmp_ngt_f32_e32 vcc, s18, v79
	v_cndmask_b32_e64 v64, v76, v64, s[2:3]
	v_add_f32_e32 v67, 1.0, v64
	v_cndmask_b32_e32 v79, v76, v84, vcc
	v_add_f32_e32 v88, 1.0, v79
	v_add_f32_e32 v89, -1.0, v67
	v_frexp_mant_f32_e32 v90, v67
	v_cvt_f64_f32_e32 v[84:85], v67
	v_add_f32_e32 v91, -1.0, v88
	v_frexp_mant_f32_e32 v92, v88
	v_cvt_f64_f32_e32 v[86:87], v88
	v_sub_f32_e32 v93, v89, v67
	v_frexp_exp_i32_f64_e32 v84, v[84:85]
	v_cmp_gt_f32_e32 vcc, s20, v90
	v_sub_f32_e32 v89, v64, v89
	v_sub_f32_e32 v85, v91, v88
	v_frexp_exp_i32_f64_e32 v86, v[86:87]
	v_cmp_gt_f32_e64 s[2:3], s20, v92
	v_add_f32_e32 v87, 1.0, v93
	v_subbrev_co_u32_e32 v84, vcc, 0, v84, vcc
	v_sub_f32_e32 v90, v79, v91
	v_add_f32_e32 v85, 1.0, v85
	v_subbrev_co_u32_e64 v86, vcc, 0, v86, s[2:3]
	v_add_f32_e32 v87, v89, v87
	v_sub_u32_e32 v89, 0, v84
	v_add_f32_e32 v85, v90, v85
	v_sub_u32_e32 v90, 0, v86
	v_ldexp_f32 v67, v67, v89
	v_ldexp_f32 v88, v88, v90
	v_ldexp_f32 v85, v85, v90
	v_add_f32_e32 v90, -1.0, v67
	v_add_f32_e32 v92, 1.0, v67
	v_ldexp_f32 v87, v87, v89
	v_add_f32_e32 v93, -1.0, v88
	v_add_f32_e32 v94, 1.0, v88
	v_add_f32_e32 v89, 1.0, v90
	v_add_f32_e32 v91, -1.0, v92
	v_add_f32_e32 v95, 1.0, v93
	v_add_f32_e32 v96, -1.0, v94
	v_sub_f32_e32 v89, v67, v89
	v_sub_f32_e32 v67, v67, v91
	v_sub_f32_e32 v91, v88, v95
	v_sub_f32_e32 v88, v88, v96
	v_add_f32_e32 v67, v87, v67
	v_add_f32_e32 v95, v87, v89
	v_add_f32_e32 v87, v85, v91
	v_add_f32_e32 v85, v85, v88
	v_add_f32_e32 v100, v92, v67
	v_add_f32_e32 v101, v94, v85
	v_rcp_f32_e32 v102, v100
	v_rcp_f32_e32 v103, v101
	v_add_f32_e32 v89, v90, v95
	v_add_f32_e32 v91, v93, v87
	v_sub_f32_e32 v88, v92, v100
	v_sub_f32_e32 v92, v94, v101
	v_mul_f32_e32 v105, v89, v102
	v_add_f32_e32 v85, v85, v92
	v_mul_f32_e32 v106, v91, v103
	v_mul_f32_e32 v92, v100, v105
	v_add_f32_e32 v67, v67, v88
	v_mul_f32_e32 v94, v101, v106
	v_fma_f32 v96, v105, v100, -v92
	v_fma_f32 v98, v106, v101, -v94
	v_fmac_f32_e32 v96, v105, v67
	v_sub_f32_e32 v90, v90, v89
	v_sub_f32_e32 v93, v93, v91
	v_fmac_f32_e32 v98, v106, v85
	v_add_f32_e32 v88, v92, v96
	v_add_f32_e32 v104, v95, v90
	v_add_f32_e32 v87, v87, v93
	v_add_f32_e32 v90, v94, v98
	v_sub_f32_e32 v93, v89, v88
	v_mov_b32_e32 v97, v88
	v_sub_f32_e32 v95, v91, v90
	v_pk_add_f32 v[88:89], v[88:89], v[92:93] neg_lo:[0,1] neg_hi:[0,1]
	v_mov_b32_e32 v99, v90
	v_pk_add_f32 v[90:91], v[90:91], v[94:95] neg_lo:[0,1] neg_hi:[0,1]
; __device__ __forceinline__ void ret_gammas(const Args& a, int l, int h, float& lgf2, float& lgb2) {
;     const float xf = a.in[8][(l * 2 + 0) * 4 + h], xb = a.in[8][(l * 2 + 1) * 4 + h];
;     lgf2 = -log1pf(expf(-xf)) * LOG2E; lgb2 = -log1pf(expf(-xb)) * LOG2E;
; __device__ __forceinline__ void phase_scan(const Args& a, unsigned char* ws, bf16* STB, int l, int vcu, int G, int tid, int z) {
;     ...
;         float lgf2, lgb2; ret_gammas(a, l, h, lgf2, lgb2);
;         const float g = __builtin_amdgcn_exp2f(128.f * (dir ? lgb2 : lgf2));
	v_pk_add_f32 v[88:89], v[88:89], v[96:97] neg_lo:[0,1] neg_hi:[0,1]
	v_pk_add_f32 v[90:91], v[90:91], v[98:99] neg_lo:[0,1] neg_hi:[0,1]
	v_add_f32_e32 v89, v104, v89
	v_add_f32_e32 v87, v87, v91
	v_add_f32_e32 v88, v88, v89
	v_add_f32_e32 v87, v90, v87
	v_add_f32_e32 v89, v93, v88
	v_add_f32_e32 v91, v95, v87
	v_mul_f32_e32 v90, v102, v89
	v_mul_f32_e32 v97, v103, v91
	v_mul_f32_e32 v92, v100, v90
	v_sub_f32_e32 v93, v93, v89
	v_add_f32_e32 v107, v105, v90
	v_mul_f32_e32 v94, v101, v97
	v_fma_f32 v96, v90, v100, -v92
	v_add_f32_e32 v104, v88, v93
	v_add_f32_e32 v108, v106, v97
	v_sub_f32_e32 v88, v107, v105
	v_fma_f32 v98, v97, v101, -v94
	v_fmac_f32_e32 v96, v90, v67
	v_sub_f32_e32 v93, v108, v106
	v_sub_f32_e32 v67, v90, v88
	v_fmac_f32_e32 v98, v97, v85
	v_add_f32_e32 v88, v92, v96
	v_sub_f32_e32 v95, v95, v91
	v_sub_f32_e32 v85, v97, v93
	v_add_f32_e32 v90, v94, v98
	v_sub_f32_e32 v93, v89, v88
	v_add_f32_e32 v87, v87, v95
	v_mov_b32_e32 v97, v88
	v_sub_f32_e32 v95, v91, v90
	v_pk_add_f32 v[88:89], v[88:89], v[92:93] neg_lo:[0,1] neg_hi:[0,1]
	v_mov_b32_e32 v99, v90
	v_pk_add_f32 v[90:91], v[90:91], v[94:95] neg_lo:[0,1] neg_hi:[0,1]
	v_pk_add_f32 v[88:89], v[88:89], v[96:97] neg_lo:[0,1] neg_hi:[0,1]
	v_pk_add_f32 v[90:91], v[90:91], v[98:99] neg_lo:[0,1] neg_hi:[0,1]
	v_add_f32_e32 v89, v104, v89
	v_add_f32_e32 v87, v87, v91
	v_add_f32_e32 v88, v88, v89
	v_add_f32_e32 v87, v90, v87
	v_add_f32_e32 v88, v93, v88
	v_add_f32_e32 v87, v95, v87
	v_mul_f32_e32 v88, v102, v88
	v_mul_f32_e32 v87, v103, v87
	v_add_f32_e32 v67, v67, v88
	v_cvt_f32_i32_e32 v84, v84
	v_add_f32_e32 v87, v85, v87
	v_add_f32_e32 v85, v107, v67
	v_cvt_f32_i32_e32 v86, v86
	v_add_f32_e32 v88, v108, v87
	v_mul_f32_e32 v90, v85, v85
	v_sub_f32_e32 v92, v85, v107
	v_mul_f32_e32 v94, v88, v88
	v_sub_f32_e32 v93, v88, v108
	v_fmamk_f32 v95, v90, 0x3e9b6dac, v77
	v_ldexp_f32 v89, v85, 1
	v_sub_f32_e32 v92, v67, v92
	v_mul_f32_e32 v85, v85, v90
	v_fmamk_f32 v96, v94, 0x3e9b6dac, v77
	v_sub_f32_e32 v93, v87, v93
	v_fmaak_f32 v67, v90, v95, 0x3f2aaada
	v_mul_f32_e32 v87, v88, v94
	v_ldexp_f32 v95, v92, 1
	v_ldexp_f32 v104, v93, 1
	v_pk_mul_f32 v[92:93], v[84:85], v[66:67]
	v_fmaak_f32 v67, v94, v96, 0x3f2aaada
	v_ldexp_f32 v91, v88, 1
	v_fma_f32 v88, v84, s21, -v92
	v_pk_mul_f32 v[96:97], v[86:87], v[66:67]
	v_fmac_f32_e32 v88, 0xb102e308, v84
	v_fma_f32 v90, v86, s21, -v96
	v_pk_add_f32 v[98:99], v[92:93], v[88:89]
	v_fmac_f32_e32 v90, 0xb102e308, v86
	v_sub_f32_e32 v67, v99, v89
	v_pk_add_f32 v[102:103], v[96:97], v[90:91]
	v_sub_f32_e32 v67, v93, v67
	v_sub_f32_e32 v85, v103, v91
	v_mov_b32_e32 v94, v92
	v_add_f32_e32 v95, v95, v67
	v_sub_f32_e32 v67, v97, v85
	v_mov_b32_e32 v84, v96
	v_pk_add_f32 v[86:87], v[98:99], v[92:93] neg_lo:[0,1] neg_hi:[0,1]
	v_pk_add_f32 v[92:93], v[102:103], v[96:97] neg_lo:[0,1] neg_hi:[0,1]
	v_pk_add_f32 v[96:97], v[98:99], v[94:95]
	v_add_f32_e32 v85, v104, v67
	v_mov_b32_e32 v89, v98
	v_mov_b32_e32 v87, v97
	v_pk_add_f32 v[106:107], v[102:103], v[84:85]
	v_mov_b32_e32 v91, v102
	v_mov_b32_e32 v104, v85
	v_pk_add_f32 v[84:85], v[88:89], v[86:87] neg_lo:[0,1] neg_hi:[0,1]
	v_pk_add_f32 v[86:87], v[88:89], v[86:87]
	v_mov_b32_e32 v93, v107
	v_pk_add_f32 v[108:109], v[86:87], v[98:99] op_sel:[1,0] op_sel_hi:[0,1] neg_lo:[0,1] neg_hi:[0,1]
	v_pk_add_f32 v[110:111], v[90:91], v[92:93] neg_lo:[0,1] neg_hi:[0,1]
	v_pk_add_f32 v[90:91], v[90:91], v[92:93]
	v_mov_b32_e32 v101, v98
	v_mov_b32_e32 v100, v95
	v_mov_b32_e32 v94, v97
	v_mov_b32_e32 v95, v87
	v_pk_add_f32 v[92:93], v[96:97], v[108:109] op_sel_hi:[1,0] neg_lo:[0,1] neg_hi:[0,1]
	v_pk_mov_b32 v[96:97], v[98:99], v[108:109] op_sel:[1,0]
	v_pk_add_f32 v[98:99], v[90:91], v[102:103] op_sel:[1,0] op_sel_hi:[0,1] neg_lo:[0,1] neg_hi:[0,1]
	v_mov_b32_e32 v88, v107
	v_mov_b32_e32 v89, v91
	v_pk_add_f32 v[94:95], v[94:95], v[96:97] neg_lo:[0,1] neg_hi:[0,1]
	v_pk_add_f32 v[96:97], v[106:107], v[98:99] op_sel_hi:[1,0] neg_lo:[0,1] neg_hi:[0,1]
	v_pk_mov_b32 v[98:99], v[102:103], v[98:99] op_sel:[1,0]
	v_mov_b32_e32 v105, v102
	v_mov_b32_e32 v92, v84
	v_pk_add_f32 v[94:95], v[100:101], v[94:95] neg_lo:[0,1] neg_hi:[0,1]
	v_pk_add_f32 v[88:89], v[88:89], v[98:99] neg_lo:[0,1] neg_hi:[0,1]
	v_mov_b32_e32 v96, v110
	v_pk_add_f32 v[92:93], v[92:93], v[94:95]
	v_pk_add_f32 v[88:89], v[104:105], v[88:89] neg_lo:[0,1] neg_hi:[0,1]
	v_pk_add_f32 v[98:99], v[92:93], v[92:93] op_sel:[0,1] op_sel_hi:[1,0]
	v_pk_add_f32 v[96:97], v[96:97], v[88:89]
	v_mov_b32_e32 v85, v87
	v_pk_add_f32 v[86:87], v[86:87], v[98:99] op_sel:[1,0] op_sel_hi:[0,1]
	v_mov_b32_e32 v95, v98
	v_pk_add_f32 v[98:99], v[96:97], v[96:97] op_sel:[0,1] op_sel_hi:[1,0]
	v_mov_b32_e32 v111, v91
	v_mov_b32_e32 v93, v86
	v_pk_add_f32 v[90:91], v[90:91], v[98:99] op_sel:[1,0] op_sel_hi:[0,1]
	v_mov_b32_e32 v89, v98
	v_pk_add_f32 v[98:99], v[92:93], v[84:85] neg_lo:[0,1] neg_hi:[0,1]
	v_mov_b32_e32 v97, v90
	v_sub_f32_e32 v67, v92, v98
	v_pk_add_f32 v[92:93], v[96:97], v[110:111] neg_lo:[0,1] neg_hi:[0,1]
	v_pk_add_f32 v[94:95], v[94:95], v[98:99] neg_lo:[0,1] neg_hi:[0,1]
	v_sub_f32_e32 v67, v84, v67
	v_sub_f32_e32 v87, v96, v92
	v_pk_add_f32 v[84:85], v[88:89], v[92:93] neg_lo:[0,1] neg_hi:[0,1]
	v_add_f32_e32 v67, v94, v67
	v_sub_f32_e32 v87, v110, v87
	v_add_f32_e32 v67, v67, v95
	v_add_f32_e32 v84, v84, v87
	v_add_f32_e32 v67, v86, v67
	v_add_f32_e32 v84, v84, v85
	v_cmp_neq_f32_e32 vcc, s19, v64
	v_add_f32_e32 v84, v90, v84
	v_cmp_lt_f32_e64 s[2:3], |v64|, s22
	v_cndmask_b32_e32 v67, v76, v67, vcc
	v_cmp_neq_f32_e32 vcc, s19, v79
	v_cndmask_b32_e64 v64, v67, v64, s[2:3]
	s_nop 0
	v_cndmask_b32_e32 v67, v76, v84, vcc
	v_cmp_lt_f32_e64 vcc, |v79|, s22
	s_nop 1
	v_cndmask_b32_e32 v67, v67, v79, vcc
	v_cmp_eq_u32_e32 vcc, 0, v78
	s_nop 1
	v_cndmask_b32_e32 v64, v67, v64, vcc
	v_mul_f32_e32 v64, 0xbfb8aa3b, v64
	v_mul_f32_e32 v64, 0x43000000, v64
	v_exp_f32_e32 v64, v64
	s_waitcnt vmcnt(0)
; __device__ __forceinline__ unsigned pkbf(float lo, float hi) { typedef __bf16 bf2_t __attribute__((ext_vector_type(2))); f32x2 v = {lo, hi}; bf2_t b = __builtin_convertvector(v, bf2_t); return __builtin_bit_cast(unsigned, b); }
; __device__ __forceinline__ void phase_scan(const Args& a, unsigned char* ws, bf16* STB, int l, int vcu, int G, int tid, int z) {
;     ...
;         for (int i = 0; i < 16; ++i) {
;             const int n = dir ? 15 - i : i;
;             u32x4 w; w.x = pkbf(c[0], c[1]); w.y = pkbf(c[2], c[3]); w.z = pkbf(c[4], c[5]); w.w = pkbf(c[6], c[7]);
;             *(u32x4*)(base + (size_t)n * cst) = w;
; #pragma unroll
;             for (int e = 0; e < 4; ++e) { c[2 * e] = bflo(kv[n][e]) + g * c[2 * e]; c[2 * e + 1] = bfhi(kv[n][e]) + g * c[2 * e + 1]; }
	v_cndmask_b32_e32 v59, v63, v59, vcc
	v_cndmask_b32_e32 v58, v62, v58, vcc
	v_cndmask_b32_e32 v57, v61, v57, vcc
	v_cndmask_b32_e32 v56, v60, v56, vcc
	v_cndmask_b32_e64 v60, 14, 1, vcc
	v_cndmask_b32_e32 v61, v19, v3, vcc
	v_cndmask_b32_e32 v62, v18, v2, vcc
	v_cndmask_b32_e32 v63, v17, v1, vcc
	v_cndmask_b32_e64 v78, 13, 2, vcc
	v_cndmask_b32_e32 v79, v27, v7, vcc
	v_cndmask_b32_e32 v84, v26, v6, vcc
	v_cndmask_b32_e32 v85, v25, v5, vcc
	v_cndmask_b32_e32 v86, v24, v4, vcc
	v_cndmask_b32_e64 v87, 12, 3, vcc
	v_cndmask_b32_e32 v88, v31, v11, vcc
	v_cndmask_b32_e32 v89, v30, v10, vcc
	v_cndmask_b32_e32 v90, v29, v9, vcc
	v_cndmask_b32_e32 v91, v28, v8, vcc
	v_cndmask_b32_e64 v92, 11, 4, vcc
	v_cndmask_b32_e32 v93, v39, v15, vcc
	v_cndmask_b32_e32 v96, v36, v12, vcc
	v_cndmask_b32_e64 v97, 10, 5, vcc
	v_cndmask_b32_e32 v98, v43, v23, vcc
	v_cndmask_b32_e32 v99, v42, v22, vcc
	v_cndmask_b32_e32 v100, v41, v21, vcc
	v_cndmask_b32_e32 v101, v40, v20, vcc
	v_cndmask_b32_e64 v102, 9, 6, vcc
	v_cndmask_b32_e32 v103, v47, v35, vcc
	v_cndmask_b32_e32 v104, v46, v34, vcc
	v_cndmask_b32_e32 v105, v45, v33, vcc
	v_cndmask_b32_e32 v106, v44, v32, vcc
	v_cndmask_b32_e32 v107, v55, v51, vcc
	v_cndmask_b32_e32 v108, v54, v50, vcc
	v_cndmask_b32_e32 v109, v53, v49, vcc
	v_cndmask_b32_e32 v110, v52, v48, vcc
	v_cndmask_b32_e32 v111, v51, v55, vcc
	v_cndmask_b32_e32 v112, v50, v54, vcc
	v_cndmask_b32_e32 v113, v49, v53, vcc
	v_cndmask_b32_e64 v115, 6, 9, vcc
	v_cndmask_b32_e32 v116, v35, v47, vcc
	v_cndmask_b32_e32 v117, v34, v46, vcc
	v_cndmask_b32_e32 v118, v33, v45, vcc
	v_cndmask_b32_e32 v119, v32, v44, vcc
	v_cndmask_b32_e64 v120, 5, 10, vcc
	v_cndmask_b32_e32 v122, v22, v42, vcc
	v_cndmask_b32_e32 v123, v21, v41, vcc
	v_cndmask_b32_e64 v125, 4, 11, vcc
	v_cndmask_b32_e64 v132, 3, 12, vcc
	v_cndmask_b32_e64 v142, 2, 13, vcc
	v_cndmask_b32_e64 v152, 1, 14, vcc
	v_cndmask_b32_e64 v162, 0, 15, vcc
	v_cndmask_b32_e32 v67, v16, v0, vcc
	v_cndmask_b32_e32 v94, v38, v14, vcc
	v_cndmask_b32_e32 v95, v37, v13, vcc
	v_cndmask_b32_e32 v114, v48, v52, vcc
	v_cndmask_b32_e32 v121, v23, v43, vcc
	v_cndmask_b32_e32 v124, v20, v40, vcc
	v_cndmask_b32_e32 v131, v15, v39, vcc
	v_cndmask_b32_e32 v129, v14, v38, vcc
	v_cndmask_b32_e32 v127, v13, v37, vcc
	v_cndmask_b32_e32 v126, v12, v36, vcc
	v_cndmask_b32_e32 v141, v11, v31, vcc
	v_cndmask_b32_e32 v139, v10, v30, vcc
	v_cndmask_b32_e32 v137, v9, v29, vcc
	v_cndmask_b32_e32 v135, v8, v28, vcc
	v_cndmask_b32_e32 v151, v7, v27, vcc
	v_cndmask_b32_e32 v149, v6, v26, vcc
	v_cndmask_b32_e32 v147, v5, v25, vcc
	v_cndmask_b32_e32 v145, v4, v24, vcc
	v_cndmask_b32_e32 v161, v3, v19, vcc
	v_cndmask_b32_e32 v159, v2, v18, vcc
	v_cndmask_b32_e32 v157, v1, v17, vcc
	v_cndmask_b32_e32 v155, v0, v16, vcc
	v_lshlrev_b32_e32 v0, 16, v56
	v_and_b32_e32 v1, 0xffff0000, v56
	v_lshlrev_b32_e32 v2, 16, v57
	v_and_b32_e32 v3, 0xffff0000, v57
	v_lshlrev_b32_e32 v4, 16, v58
	v_and_b32_e32 v5, 0xffff0000, v58
	v_lshlrev_b32_e32 v6, 16, v59
	v_and_b32_e32 v7, 0xffff0000, v59
	v_mad_i64_i32 v[8:9], s[2:3], v60, s10, 0
	v_lshlrev_b32_e32 v12, 16, v63
	v_and_b32_e32 v13, 0xffff0000, v63
	v_lshlrev_b32_e32 v14, 16, v62
	v_and_b32_e32 v15, 0xffff0000, v62
	v_lshlrev_b32_e32 v16, 16, v61
	v_and_b32_e32 v17, 0xffff0000, v61
	v_mad_i64_i32 v[18:19], s[2:3], v78, s10, 0
	v_lshlrev_b32_e32 v20, 16, v86
	v_and_b32_e32 v21, 0xffff0000, v86
	v_lshlrev_b32_e32 v22, 16, v85
	v_and_b32_e32 v23, 0xffff0000, v85
	v_lshlrev_b32_e32 v24, 16, v84
	v_and_b32_e32 v25, 0xffff0000, v84
	v_lshlrev_b32_e32 v26, 16, v79
	v_and_b32_e32 v27, 0xffff0000, v79
	v_mad_i64_i32 v[28:29], s[2:3], v87, s10, 0
	v_lshlrev_b32_e32 v30, 16, v91
	v_and_b32_e32 v31, 0xffff0000, v91
	v_lshlrev_b32_e32 v32, 16, v90
	v_and_b32_e32 v33, 0xffff0000, v90
	v_lshlrev_b32_e32 v34, 16, v89
	v_and_b32_e32 v35, 0xffff0000, v89
	v_lshlrev_b32_e32 v36, 16, v88
	v_and_b32_e32 v37, 0xffff0000, v88
	v_mad_i64_i32 v[38:39], s[2:3], v92, s10, 0
	v_lshlrev_b32_e32 v40, 16, v96
	v_and_b32_e32 v41, 0xffff0000, v96
	v_lshlrev_b32_e32 v46, 16, v93
	v_and_b32_e32 v47, 0xffff0000, v93
	v_mad_i64_i32 v[48:49], s[2:3], v97, s10, 0
	v_lshlrev_b32_e32 v50, 16, v101
	v_and_b32_e32 v51, 0xffff0000, v101
	v_lshlrev_b32_e32 v52, 16, v100
	v_and_b32_e32 v53, 0xffff0000, v100
	v_lshlrev_b32_e32 v54, 16, v99
	v_and_b32_e32 v55, 0xffff0000, v99
	v_lshlrev_b32_e32 v56, 16, v98
	v_and_b32_e32 v57, 0xffff0000, v98
	v_mad_i64_i32 v[58:59], s[2:3], v102, s10, 0
	v_lshlrev_b32_e32 v60, 16, v106
	v_and_b32_e32 v61, 0xffff0000, v106
	v_lshlrev_b32_e32 v62, 16, v105
	v_and_b32_e32 v63, 0xffff0000, v105
	v_lshlrev_b32_e32 v78, 16, v104
	v_and_b32_e32 v79, 0xffff0000, v104
	v_lshlrev_b32_e32 v84, 16, v103
	v_and_b32_e32 v85, 0xffff0000, v103
	v_lshlrev_b32_e32 v86, 16, v110
	v_and_b32_e32 v87, 0xffff0000, v110
	v_lshlrev_b32_e32 v88, 16, v109
	v_and_b32_e32 v89, 0xffff0000, v109
	v_lshlrev_b32_e32 v90, 16, v108
	v_and_b32_e32 v91, 0xffff0000, v108
	v_lshlrev_b32_e32 v92, 16, v107
	v_and_b32_e32 v93, 0xffff0000, v107
	v_lshlrev_b32_e32 v96, 16, v113
	v_and_b32_e32 v97, 0xffff0000, v113
	v_lshlrev_b32_e32 v98, 16, v112
	v_and_b32_e32 v99, 0xffff0000, v112
	v_lshlrev_b32_e32 v100, 16, v111
	v_and_b32_e32 v101, 0xffff0000, v111
	v_mad_i64_i32 v[102:103], s[2:3], v115, s10, 0
	v_lshlrev_b32_e32 v104, 16, v119
	v_and_b32_e32 v105, 0xffff0000, v119
	v_lshlrev_b32_e32 v106, 16, v118
	v_and_b32_e32 v107, 0xffff0000, v118
	v_lshlrev_b32_e32 v108, 16, v117
	v_and_b32_e32 v109, 0xffff0000, v117
	v_lshlrev_b32_e32 v110, 16, v116
	v_and_b32_e32 v111, 0xffff0000, v116
	v_mad_i64_i32 v[112:113], s[2:3], v120, s10, 0
	v_lshlrev_b32_e32 v116, 16, v123
; __device__ __forceinline__ unsigned pkbf(float lo, float hi) { typedef __bf16 bf2_t __attribute__((ext_vector_type(2))); f32x2 v = {lo, hi}; bf2_t b = __builtin_convertvector(v, bf2_t); return __builtin_bit_cast(unsigned, b); }
; __device__ __forceinline__ void phase_scan(const Args& a, unsigned char* ws, bf16* STB, int l, int vcu, int G, int tid, int z) {
;     ...
;         for (int i = 0; i < 16; ++i) {
;             const int n = dir ? 15 - i : i;
;             u32x4 w; w.x = pkbf(c[0], c[1]); w.y = pkbf(c[2], c[3]); w.z = pkbf(c[4], c[5]); w.w = pkbf(c[6], c[7]);
;             *(u32x4*)(base + (size_t)n * cst) = w;
; #pragma unroll
;             for (int e = 0; e < 4; ++e) { c[2 * e] = bflo(kv[n][e]) + g * c[2 * e]; c[2 * e + 1] = bfhi(kv[n][e]) + g * c[2 * e + 1]; }
;         }
	v_and_b32_e32 v117, 0xffff0000, v123
	v_lshlrev_b32_e32 v118, 16, v122
	v_and_b32_e32 v119, 0xffff0000, v122
	v_mad_i64_i32 v[122:123], s[2:3], v125, s10, 0
	v_mad_i64_i32 v[132:133], s[2:3], v132, s10, 0
	v_mad_i64_i32 v[142:143], s[2:3], v142, s10, 0
	v_mad_i64_i32 v[152:153], s[2:3], v152, s10, 0
	v_mad_i64_i32 v[162:163], s[2:3], v162, s10, 0
	v_lshl_add_u64 v[8:9], v[8:9], 1, v[72:73]
	v_lshl_add_u64 v[18:19], v[18:19], 1, v[72:73]
	v_lshl_add_u64 v[28:29], v[28:29], 1, v[72:73]
	v_lshl_add_u64 v[38:39], v[38:39], 1, v[72:73]
	v_lshl_add_u64 v[48:49], v[48:49], 1, v[72:73]
	v_lshl_add_u64 v[58:59], v[58:59], 1, v[72:73]
	v_lshl_add_u64 v[102:103], v[102:103], 1, v[72:73]
	v_lshl_add_u64 v[112:113], v[112:113], 1, v[72:73]
	v_lshl_add_u64 v[122:123], v[122:123], 1, v[72:73]
	v_lshl_add_u64 v[132:133], v[132:133], 1, v[72:73]
	v_lshl_add_u64 v[142:143], v[142:143], 1, v[72:73]
	v_lshl_add_u64 v[152:153], v[152:153], 1, v[72:73]
	v_lshl_add_u64 v[72:73], v[162:163], 1, v[72:73]
	v_mul_f32_e32 v162, 0, v64
	v_lshlrev_b32_e32 v10, 16, v67
	v_and_b32_e32 v11, 0xffff0000, v67
	v_pk_add_f32 v[164:165], v[162:163], v[0:1] op_sel_hi:[0,1]
	v_pk_add_f32 v[166:167], v[162:163], v[2:3] op_sel_hi:[0,1]
	v_pk_add_f32 v[4:5], v[162:163], v[4:5] op_sel_hi:[0,1]
	v_pk_add_f32 v[6:7], v[162:163], v[6:7] op_sel_hi:[0,1]
	v_cvt_pk_bf16_f32 v0, v164, v165
	v_cvt_pk_bf16_f32 v1, v166, v167
	v_cvt_pk_bf16_f32 v2, v4, v5
	v_cvt_pk_bf16_f32 v3, v6, v7
	v_pk_fma_f32 v[10:11], v[64:65], v[164:165], v[10:11] op_sel_hi:[0,1,1]
	v_pk_fma_f32 v[12:13], v[64:65], v[166:167], v[12:13] op_sel_hi:[0,1,1]
	v_pk_fma_f32 v[4:5], v[64:65], v[4:5], v[14:15] op_sel_hi:[0,1,1]
	v_pk_fma_f32 v[6:7], v[64:65], v[6:7], v[16:17] op_sel_hi:[0,1,1]
	global_store_dwordx4 v[8:9], v[0:3], off
	v_pk_fma_f32 v[8:9], v[64:65], v[10:11], v[20:21] op_sel_hi:[0,1,1]
	v_lshlrev_b32_e32 v42, 16, v95
	v_cvt_pk_bf16_f32 v0, v10, v11
	v_cvt_pk_bf16_f32 v1, v12, v13
	v_cvt_pk_bf16_f32 v2, v4, v5
	v_cvt_pk_bf16_f32 v3, v6, v7
	v_pk_fma_f32 v[10:11], v[64:65], v[12:13], v[22:23] op_sel_hi:[0,1,1]
	v_pk_fma_f32 v[4:5], v[64:65], v[4:5], v[24:25] op_sel_hi:[0,1,1]
	v_pk_fma_f32 v[6:7], v[64:65], v[6:7], v[26:27] op_sel_hi:[0,1,1]
	v_and_b32_e32 v43, 0xffff0000, v95
	v_lshlrev_b32_e32 v44, 16, v94
	v_and_b32_e32 v45, 0xffff0000, v94
	global_store_dwordx4 v[18:19], v[0:3], off
	v_lshlrev_b32_e32 v94, 16, v114
	v_and_b32_e32 v95, 0xffff0000, v114
	v_cvt_pk_bf16_f32 v0, v8, v9
	v_cvt_pk_bf16_f32 v1, v10, v11
	v_cvt_pk_bf16_f32 v2, v4, v5
	v_cvt_pk_bf16_f32 v3, v6, v7
	v_pk_fma_f32 v[8:9], v[64:65], v[8:9], v[30:31] op_sel_hi:[0,1,1]
	v_pk_fma_f32 v[10:11], v[64:65], v[10:11], v[32:33] op_sel_hi:[0,1,1]
	v_pk_fma_f32 v[4:5], v[64:65], v[4:5], v[34:35] op_sel_hi:[0,1,1]
	v_pk_fma_f32 v[6:7], v[64:65], v[6:7], v[36:37] op_sel_hi:[0,1,1]
	global_store_dwordx4 v[28:29], v[0:3], off
	v_lshlrev_b32_e32 v114, 16, v124
	v_and_b32_e32 v115, 0xffff0000, v124
	v_cvt_pk_bf16_f32 v0, v8, v9
	v_cvt_pk_bf16_f32 v1, v10, v11
	v_cvt_pk_bf16_f32 v2, v4, v5
	v_cvt_pk_bf16_f32 v3, v6, v7
	v_pk_fma_f32 v[8:9], v[64:65], v[8:9], v[40:41] op_sel_hi:[0,1,1]
	v_pk_fma_f32 v[10:11], v[64:65], v[10:11], v[42:43] op_sel_hi:[0,1,1]
	v_pk_fma_f32 v[4:5], v[64:65], v[4:5], v[44:45] op_sel_hi:[0,1,1]
	v_pk_fma_f32 v[6:7], v[64:65], v[6:7], v[46:47] op_sel_hi:[0,1,1]
	global_store_dwordx4 v[38:39], v[0:3], off
	v_lshlrev_b32_e32 v120, 16, v121
	v_and_b32_e32 v121, 0xffff0000, v121
	v_cvt_pk_bf16_f32 v0, v8, v9
	v_cvt_pk_bf16_f32 v1, v10, v11
	v_cvt_pk_bf16_f32 v2, v4, v5
	v_cvt_pk_bf16_f32 v3, v6, v7
	v_pk_fma_f32 v[8:9], v[64:65], v[8:9], v[50:51] op_sel_hi:[0,1,1]
	v_pk_fma_f32 v[10:11], v[64:65], v[10:11], v[52:53] op_sel_hi:[0,1,1]
	v_pk_fma_f32 v[4:5], v[64:65], v[4:5], v[54:55] op_sel_hi:[0,1,1]
	v_pk_fma_f32 v[6:7], v[64:65], v[6:7], v[56:57] op_sel_hi:[0,1,1]
	global_store_dwordx4 v[48:49], v[0:3], off
	v_lshlrev_b32_e32 v124, 16, v126
	v_and_b32_e32 v125, 0xffff0000, v126
	v_cvt_pk_bf16_f32 v0, v8, v9
	v_cvt_pk_bf16_f32 v1, v10, v11
	v_cvt_pk_bf16_f32 v2, v4, v5
	v_cvt_pk_bf16_f32 v3, v6, v7
	v_pk_fma_f32 v[8:9], v[64:65], v[8:9], v[60:61] op_sel_hi:[0,1,1]
	v_pk_fma_f32 v[10:11], v[64:65], v[10:11], v[62:63] op_sel_hi:[0,1,1]
	v_pk_fma_f32 v[4:5], v[64:65], v[4:5], v[78:79] op_sel_hi:[0,1,1]
	v_pk_fma_f32 v[6:7], v[64:65], v[6:7], v[84:85] op_sel_hi:[0,1,1]
	global_store_dwordx4 v[58:59], v[0:3], off
	v_lshlrev_b32_e32 v126, 16, v127
	v_and_b32_e32 v127, 0xffff0000, v127
	v_cvt_pk_bf16_f32 v0, v8, v9
	v_cvt_pk_bf16_f32 v1, v10, v11
	v_cvt_pk_bf16_f32 v2, v4, v5
	v_cvt_pk_bf16_f32 v3, v6, v7
	v_pk_fma_f32 v[8:9], v[64:65], v[8:9], v[86:87] op_sel_hi:[0,1,1]
; __device__ __forceinline__ unsigned pkbf(float lo, float hi) { typedef __bf16 bf2_t __attribute__((ext_vector_type(2))); f32x2 v = {lo, hi}; bf2_t b = __builtin_convertvector(v, bf2_t); return __builtin_bit_cast(unsigned, b); }
; __device__ __forceinline__ void phase_scan(const Args& a, unsigned char* ws, bf16* STB, int l, int vcu, int G, int tid, int z) {
;     ...
;         for (int i = 0; i < 16; ++i) {
;             const int n = dir ? 15 - i : i;
;             u32x4 w; w.x = pkbf(c[0], c[1]); w.y = pkbf(c[2], c[3]); w.z = pkbf(c[4], c[5]); w.w = pkbf(c[6], c[7]);
;             *(u32x4*)(base + (size_t)n * cst) = w;
; #pragma unroll
;             for (int e = 0; e < 4; ++e) { c[2 * e] = bflo(kv[n][e]) + g * c[2 * e]; c[2 * e + 1] = bfhi(kv[n][e]) + g * c[2 * e + 1]; }
;         }
	v_pk_fma_f32 v[10:11], v[64:65], v[10:11], v[88:89] op_sel_hi:[0,1,1]
	v_pk_fma_f32 v[4:5], v[64:65], v[4:5], v[90:91] op_sel_hi:[0,1,1]
	v_pk_fma_f32 v[6:7], v[64:65], v[6:7], v[92:93] op_sel_hi:[0,1,1]
	global_store_dwordx4 v[70:71], v[0:3], off
	v_lshlrev_b32_e32 v128, 16, v129
	v_and_b32_e32 v129, 0xffff0000, v129
	v_cvt_pk_bf16_f32 v0, v8, v9
	v_cvt_pk_bf16_f32 v1, v10, v11
	v_cvt_pk_bf16_f32 v2, v4, v5
	v_cvt_pk_bf16_f32 v3, v6, v7
	v_pk_fma_f32 v[8:9], v[64:65], v[8:9], v[94:95] op_sel_hi:[0,1,1]
	v_pk_fma_f32 v[10:11], v[64:65], v[10:11], v[96:97] op_sel_hi:[0,1,1]
	v_pk_fma_f32 v[4:5], v[64:65], v[4:5], v[98:99] op_sel_hi:[0,1,1]
	v_pk_fma_f32 v[6:7], v[64:65], v[6:7], v[100:101] op_sel_hi:[0,1,1]
	global_store_dwordx4 v[68:69], v[0:3], off
	v_lshlrev_b32_e32 v130, 16, v131
	v_and_b32_e32 v131, 0xffff0000, v131
	v_cvt_pk_bf16_f32 v0, v8, v9
	v_cvt_pk_bf16_f32 v1, v10, v11
	v_cvt_pk_bf16_f32 v2, v4, v5
	v_cvt_pk_bf16_f32 v3, v6, v7
	v_pk_fma_f32 v[8:9], v[64:65], v[8:9], v[104:105] op_sel_hi:[0,1,1]
	v_pk_fma_f32 v[10:11], v[64:65], v[10:11], v[106:107] op_sel_hi:[0,1,1]
	v_pk_fma_f32 v[4:5], v[64:65], v[4:5], v[108:109] op_sel_hi:[0,1,1]
	v_pk_fma_f32 v[6:7], v[64:65], v[6:7], v[110:111] op_sel_hi:[0,1,1]
	global_store_dwordx4 v[102:103], v[0:3], off
	v_lshlrev_b32_e32 v134, 16, v135
	v_and_b32_e32 v135, 0xffff0000, v135
	v_cvt_pk_bf16_f32 v0, v8, v9
	v_cvt_pk_bf16_f32 v1, v10, v11
	v_cvt_pk_bf16_f32 v2, v4, v5
	v_cvt_pk_bf16_f32 v3, v6, v7
	v_pk_fma_f32 v[8:9], v[64:65], v[8:9], v[114:115] op_sel_hi:[0,1,1]
	v_pk_fma_f32 v[10:11], v[64:65], v[10:11], v[116:117] op_sel_hi:[0,1,1]
	v_pk_fma_f32 v[4:5], v[64:65], v[4:5], v[118:119] op_sel_hi:[0,1,1]
	v_pk_fma_f32 v[6:7], v[64:65], v[6:7], v[120:121] op_sel_hi:[0,1,1]
	v_lshlrev_b32_e32 v136, 16, v137
	v_and_b32_e32 v137, 0xffff0000, v137
	v_lshlrev_b32_e32 v138, 16, v139
	v_and_b32_e32 v139, 0xffff0000, v139
	v_lshlrev_b32_e32 v140, 16, v141
	v_and_b32_e32 v141, 0xffff0000, v141
	global_store_dwordx4 v[112:113], v[0:3], off
	v_lshlrev_b32_e32 v144, 16, v145
	v_and_b32_e32 v145, 0xffff0000, v145
	v_cvt_pk_bf16_f32 v0, v8, v9
	v_cvt_pk_bf16_f32 v1, v10, v11
	v_cvt_pk_bf16_f32 v2, v4, v5
	v_cvt_pk_bf16_f32 v3, v6, v7
	v_pk_fma_f32 v[8:9], v[64:65], v[8:9], v[124:125] op_sel_hi:[0,1,1]
	v_pk_fma_f32 v[10:11], v[64:65], v[10:11], v[126:127] op_sel_hi:[0,1,1]
	v_pk_fma_f32 v[4:5], v[64:65], v[4:5], v[128:129] op_sel_hi:[0,1,1]
	v_pk_fma_f32 v[6:7], v[64:65], v[6:7], v[130:131] op_sel_hi:[0,1,1]
	v_lshlrev_b32_e32 v146, 16, v147
	v_and_b32_e32 v147, 0xffff0000, v147
	v_lshlrev_b32_e32 v148, 16, v149
	v_and_b32_e32 v149, 0xffff0000, v149
	v_lshlrev_b32_e32 v150, 16, v151
	v_and_b32_e32 v151, 0xffff0000, v151
	global_store_dwordx4 v[122:123], v[0:3], off
	v_lshlrev_b32_e32 v154, 16, v155
	v_and_b32_e32 v155, 0xffff0000, v155
	v_cvt_pk_bf16_f32 v0, v8, v9
	v_cvt_pk_bf16_f32 v1, v10, v11
	v_cvt_pk_bf16_f32 v2, v4, v5
	v_cvt_pk_bf16_f32 v3, v6, v7
	v_pk_fma_f32 v[8:9], v[64:65], v[8:9], v[134:135] op_sel_hi:[0,1,1]
	v_pk_fma_f32 v[10:11], v[64:65], v[10:11], v[136:137] op_sel_hi:[0,1,1]
	v_pk_fma_f32 v[4:5], v[64:65], v[4:5], v[138:139] op_sel_hi:[0,1,1]
	v_pk_fma_f32 v[6:7], v[64:65], v[6:7], v[140:141] op_sel_hi:[0,1,1]
	v_lshlrev_b32_e32 v156, 16, v157
	v_and_b32_e32 v157, 0xffff0000, v157
	v_lshlrev_b32_e32 v158, 16, v159
	v_and_b32_e32 v159, 0xffff0000, v159
	v_lshlrev_b32_e32 v160, 16, v161
	v_and_b32_e32 v161, 0xffff0000, v161
	global_store_dwordx4 v[132:133], v[0:3], off
	s_nop 1
	v_cvt_pk_bf16_f32 v0, v8, v9
	v_cvt_pk_bf16_f32 v1, v10, v11
	v_cvt_pk_bf16_f32 v2, v4, v5
	v_cvt_pk_bf16_f32 v3, v6, v7
	v_pk_fma_f32 v[8:9], v[64:65], v[8:9], v[144:145] op_sel_hi:[0,1,1]
	v_pk_fma_f32 v[10:11], v[64:65], v[10:11], v[146:147] op_sel_hi:[0,1,1]
	v_pk_fma_f32 v[4:5], v[64:65], v[4:5], v[148:149] op_sel_hi:[0,1,1]
	v_pk_fma_f32 v[6:7], v[64:65], v[6:7], v[150:151] op_sel_hi:[0,1,1]
	global_store_dwordx4 v[142:143], v[0:3], off
	s_nop 1
	v_cvt_pk_bf16_f32 v0, v8, v9
	v_cvt_pk_bf16_f32 v1, v10, v11
	v_cvt_pk_bf16_f32 v2, v4, v5
	v_cvt_pk_bf16_f32 v3, v6, v7
	v_pk_fma_f32 v[8:9], v[64:65], v[8:9], v[154:155] op_sel_hi:[0,1,1]
	v_pk_fma_f32 v[10:11], v[64:65], v[10:11], v[156:157] op_sel_hi:[0,1,1]
	v_pk_fma_f32 v[4:5], v[64:65], v[4:5], v[158:159] op_sel_hi:[0,1,1]
	v_pk_fma_f32 v[6:7], v[64:65], v[6:7], v[160:161] op_sel_hi:[0,1,1]
	global_store_dwordx4 v[152:153], v[0:3], off
	s_nop 1
	v_cvt_pk_bf16_f32 v0, v8, v9
	v_cvt_pk_bf16_f32 v1, v10, v11
	v_cvt_pk_bf16_f32 v2, v4, v5
	v_cvt_pk_bf16_f32 v3, v6, v7
	global_store_dwordx4 v[72:73], v[0:3], off
	s_andn2_b64 exec, exec, s[14:15]
	s_cbranch_execnz .LBB0_1292

; #define LAS __attribute__((address_space(3)))
; __device__ __forceinline__ void ret_gammas(const Args& a, int l, int h, float& lgf2, float& lgb2) {
;     const float xf = a.in[8][(l * 2 + 0) * 4 + h], xb = a.in[8][(l * 2 + 1) * 4 + h];
;     lgf2 = -log1pf(expf(-xf)) * LOG2E; lgb2 = -log1pf(expf(-xb)) * LOG2E;
; __device__ __forceinline__ void r2_unit(const Args& a, unsigned char* ws, bf16* STB, LAS unsigned char* lds, int l, int unit, int tid, int wid, int lane, int dry) {
;     ...
;     const int n = unit & 15, h = (unit >> 4) & 3, b = unit >> 6;
;     float lgf2, lgb2; ret_gammas(a, l, h, lgf2, lgb2);
;     bf16* P = (bf16*)(ws + WS_P);
;     const bf16* kp = P + (size_t)(b * SEQ + n * 128) * NIN + 512 + h * 128;
;     const bf16* sp = STB + ((size_t)((b * 4 + h) * 16 + n) * 2) * 16384;
;     LAS unsigned char* KT = lds, * VT = lds + 32768, * SF = lds + 65536, * SB = lds + 98304;
; #pragma unroll
;     for (int i = 0; i < 4; ++i) {
;         const int c = tid + 512 * i, row = c >> 4, ch = c & 15; const unsigned o = offb(row, ch);
;         const u32x4 kv = *(const u32x4*)(kp + (size_t)row * NIN + ch * 8), vv = *(const u32x4*)(kp + 512 + (size_t)row * NIN + ch * 8);
;         const u32x4 sf = *(const u32x4*)(sp + row * 128 + ch * 8), sb = *(const u32x4*)(sp + 16384 + row * 128 + ch * 8);
.LBB0_1392:
	s_bfe_u32 s72, s69, 0x20004
	s_lshl_b32 s2, s72, 2
	v_mov_b32_e32 v131, v199
	v_mov_b32_e32 v52, v176
	v_mov_b32_e32 v0, s2
	s_waitcnt lgkmcnt(0)
	s_load_dword s100, s[40:41], s2 offset:0x20
	s_load_dword s101, s[40:41], s2 offset:0x30
	s_and_b32 s3, s69, 15
	s_ashr_i32 s2, s69, 6
	s_lshl_b32 s6, s2, 11
	s_lshl_b32 s10, s3, 7
	s_or_b32 s6, s6, s10
	s_mul_hi_i32 s7, s6, 0x1c00
	s_mulk_i32 s6, 0x1c00
	s_add_u32 s6, s50, s6
	s_addc_u32 s7, s51, s7
	s_lshl_b32 s52, s72, 8
	s_add_u32 s6, s6, s52
	v_and_b32_e32 v68, 15, v52
	s_addc_u32 s7, s7, 0
	s_and_b32 s8, s69, 0xffffffc0
	s_lshl_b32 s9, s72, 4
	v_lshlrev_b32_e32 v124, 4, v68
	s_or_b32 s8, s9, s8
	v_lshl_add_u64 v[8:9], s[6:7], 0, v[124:125]
	s_or_b32 s6, s8, s3
	s_ashr_i32 s7, s6, 31
	s_lshl_b64 s[6:7], s[6:7], 16
	v_readlane_b32 s3, v238, 11
	s_add_u32 s6, s3, s6
	s_mov_b32 s3, 0xbfb8aa3b
	s_addc_u32 s7, s73, s7
	v_ashrrev_i32_e32 v69, 4, v52
	v_mad_i64_i32 v[4:5], s[8:9], v69, s1, v[8:9]
	s_mov_b32 s8, 0x3f2aaaab
	s_mov_b64 s[4:5], 0x8000
	global_load_dwordx4 v[0:3], v[4:5], off offset:1024
	s_nop 0
	global_load_dwordx4 v[4:7], v[4:5], off offset:2048
	v_add_u32_e32 v36, 0x400, v52
	v_ashrrev_i32_e32 v73, 4, v36
	v_lshlrev_b32_e32 v44, 7, v73
	v_ashrrev_i32_e32 v45, 31, v44
	v_lshlrev_b64 v[48:49], 1, v[44:45]
	v_ashrrev_i32_e32 v94, 5, v131
	v_lshlrev_b32_e32 v128, 3, v94
	v_ashrrev_i32_e32 v129, 31, v128
	v_lshlrev_b32_e32 v130, 2, v94
	s_waitcnt lgkmcnt(0)
	v_mov_b32_e32 v12, s100
	v_mov_b32_e32 v70, s101
	v_mul_f32_e32 v10, 0xbfb8aa3b, v12
	v_fma_f32 v11, v12, s3, -v10
	v_rndne_f32_e32 v13, v10
	v_fmac_f32_e32 v11, 0xb2a5705f, v12
	v_sub_f32_e32 v10, v10, v13
	v_add_f32_e32 v10, v10, v11
	v_cvt_i32_f32_e32 v13, v13
	v_exp_f32_e32 v14, v10
	v_lshl_add_u64 v[10:11], s[6:7], 0, v[124:125]
	s_mov_b32 s6, 0x42ce8ed0
	v_cmp_nlt_f32_e32 vcc, s6, v12
	v_ldexp_f32 v13, v14, v13
	s_mov_b32 s7, 0xc2b17218
	v_cndmask_b32_e32 v13, 0, v13, vcc
	v_cmp_ngt_f32_e32 vcc, s7, v12
	v_lshl_add_u64 v[60:61], v[10:11], 0, s[4:5]
	v_mad_i64_i32 v[40:41], s[4:5], v73, s1, v[8:9]
	v_cndmask_b32_e32 v71, v134, v13, vcc
	v_add_f32_e32 v14, 1.0, v71
	v_add_f32_e32 v15, -1.0, v14
	v_frexp_mant_f32_e32 v16, v14
	v_cvt_f64_f32_e32 v[12:13], v14
	v_sub_f32_e32 v17, v15, v14
	v_frexp_exp_i32_f64_e32 v12, v[12:13]
	v_cmp_gt_f32_e32 vcc, s8, v16
	v_sub_f32_e32 v15, v71, v15
	v_add_f32_e32 v13, 1.0, v17
	v_subbrev_co_u32_e32 v12, vcc, 0, v12, vcc
	v_add_f32_e32 v13, v15, v13
	v_sub_u32_e32 v15, 0, v12
	v_cvt_f32_i32_e32 v12, v12
	v_ldexp_f32 v14, v14, v15
	v_ldexp_f32 v13, v13, v15
	v_add_f32_e32 v15, -1.0, v14
	v_add_f32_e32 v16, 1.0, v14
	v_add_f32_e32 v17, 1.0, v15
	v_add_f32_e32 v18, -1.0, v16
	v_sub_f32_e32 v17, v14, v17
	v_sub_f32_e32 v14, v14, v18
	v_mul_f32_e32 v18, 0x3f317218, v12
	v_add_f32_e32 v17, v13, v17
	v_add_f32_e32 v13, v13, v14
	v_fma_f32 v14, v12, s60, -v18
	v_add_f32_e32 v19, v15, v17
	v_add_f32_e32 v20, v16, v13
	v_fmac_f32_e32 v14, 0xb102e308, v12
	v_sub_f32_e32 v12, v15, v19
	v_sub_f32_e32 v15, v16, v20
	v_rcp_f32_e32 v16, v20
	v_add_f32_e32 v21, v18, v14
	v_add_f32_e32 v13, v13, v15
	v_sub_f32_e32 v15, v21, v18
	v_sub_f32_e32 v14, v14, v15
	v_mul_f32_e32 v15, v19, v16
	v_add_f32_e32 v12, v17, v12
	v_mul_f32_e32 v17, v20, v15
	v_fma_f32 v18, v15, v20, -v17
	v_fmac_f32_e32 v18, v15, v13
	v_add_f32_e32 v22, v17, v18
	v_sub_f32_e32 v23, v19, v22
	v_sub_f32_e32 v17, v22, v17
	v_sub_f32_e32 v19, v19, v23
	v_sub_f32_e32 v17, v17, v18
	v_sub_f32_e32 v18, v19, v22
	v_add_f32_e32 v12, v12, v18
	v_add_f32_e32 v12, v17, v12
	v_add_f32_e32 v17, v23, v12
	v_mul_f32_e32 v18, v16, v17
	v_sub_f32_e32 v19, v23, v17
	v_mul_f32_e32 v22, v20, v18
	v_add_f32_e32 v12, v12, v19
	v_add_f32_e32 v19, v15, v18
	v_fma_f32 v20, v18, v20, -v22
	v_sub_f32_e32 v15, v19, v15
	v_fmac_f32_e32 v20, v18, v13
	v_sub_f32_e32 v13, v18, v15
	v_add_f32_e32 v15, v22, v20
	v_sub_f32_e32 v18, v15, v22
	v_sub_f32_e32 v22, v17, v15
	v_sub_f32_e32 v17, v17, v22
	v_sub_f32_e32 v15, v17, v15
	v_sub_f32_e32 v18, v18, v20
	v_add_f32_e32 v12, v12, v15
	v_add_f32_e32 v12, v18, v12
	v_add_f32_e32 v12, v22, v12
	v_mul_f32_e32 v12, v16, v12
	v_add_f32_e32 v12, v13, v12
	v_add_f32_e32 v13, v19, v12
	v_mul_f32_e32 v15, v13, v13
	v_fmamk_f32 v18, v15, 0x3e9b6dac, v135
	v_sub_f32_e32 v16, v13, v19
	v_ldexp_f32 v17, v13, 1
	v_mul_f32_e32 v13, v13, v15
	v_fmaak_f32 v15, v15, v18, 0x3f2aaada
	v_mul_f32_e32 v13, v13, v15
	v_add_f32_e32 v15, v17, v13
	v_sub_f32_e32 v12, v12, v16
	v_sub_f32_e32 v16, v15, v17
	v_ldexp_f32 v12, v12, 1
	v_sub_f32_e32 v13, v13, v16
	v_add_f32_e32 v12, v12, v13
	v_add_f32_e32 v13, v15, v12
	v_sub_f32_e32 v15, v13, v15
	v_add_f32_e32 v53, v21, v13
	v_sub_f32_e32 v12, v12, v15
	v_sub_f32_e32 v15, v53, v21
	v_sub_f32_e32 v16, v53, v15
	v_add_f32_e32 v54, v14, v12
	v_sub_f32_e32 v13, v13, v15
	v_sub_f32_e32 v15, v21, v16
	v_sub_f32_e32 v16, v54, v14
	v_add_f32_e32 v55, v13, v15
	v_sub_f32_e32 v13, v54, v16
	v_sub_f32_e32 v12, v12, v16
	v_sub_f32_e32 v13, v14, v13
	v_add_f32_e32 v62, v12, v13
	v_lshlrev_b32_e32 v12, 7, v69
	v_ashrrev_i32_e32 v13, 31, v12
	v_lshlrev_b64 v[16:17], 1, v[12:13]
	v_lshl_add_u64 v[12:13], v[10:11], 0, v[16:17]
	v_add_u32_e32 v20, 0x200, v52
	global_load_dwordx4 v[12:15], v[12:13], off
	v_lshl_add_u64 v[16:17], v[60:61], 0, v[16:17]
	v_ashrrev_i32_e32 v72, 4, v20
	global_load_dwordx4 v[16:19], v[16:17], off
	v_lshlrev_b32_e32 v28, 7, v72
	v_ashrrev_i32_e32 v29, 31, v28
	v_mad_i64_i32 v[24:25], s[4:5], v72, s1, v[8:9]
	v_lshlrev_b64 v[32:33], 1, v[28:29]
	global_load_dwordx4 v[20:23], v[24:25], off offset:1024
	s_nop 0
	global_load_dwordx4 v[24:27], v[24:25], off offset:2048
	v_lshl_add_u64 v[28:29], v[10:11], 0, v[32:33]
	global_load_dwordx4 v[28:31], v[28:29], off
	v_lshl_add_u64 v[32:33], v[60:61], 0, v[32:33]
	global_load_dwordx4 v[32:35], v[32:33], off
	s_nop 0
	global_load_dwordx4 v[36:39], v[40:41], off offset:1024
	s_nop 0
	global_load_dwordx4 v[40:43], v[40:41], off offset:2048
	v_lshl_add_u64 v[44:45], v[10:11], 0, v[48:49]
	global_load_dwordx4 v[44:47], v[44:45], off
	v_lshl_add_u64 v[48:49], v[60:61], 0, v[48:49]
	global_load_dwordx4 v[48:51], v[48:49], off
	v_add_u32_e32 v52, 0x600, v52
	v_add_f32_e32 v63, v54, v55
	v_ashrrev_i32_e32 v74, 4, v52
	v_add_f32_e32 v64, v53, v63
	v_mad_i64_i32 v[8:9], s[4:5], v74, s1, v[8:9]
	v_sub_f32_e32 v65, v64, v53
	global_load_dwordx4 v[52:55], v[8:9], off offset:1024
	global_load_dwordx4 v[56:59], v[8:9], off offset:2048
	v_sub_f32_e32 v8, v63, v65
	v_add_f32_e32 v8, v62, v8
	v_add_f32_e32 v75, v64, v8
	s_waitcnt vmcnt(14)
; #define LAS __attribute__((address_space(3)))
; __device__ __forceinline__ int crow(int r, int hi) { return (r & 3) + 8 * (r >> 2) + 4 * hi; }
; __device__ __forceinline__ void r2_unit(const Args& a, unsigned char* ws, bf16* STB, LAS unsigned char* lds, int l, int unit, int tid, int wid, int lane, int dry) {
;     ...
; #pragma unroll
;     for (int i = 0; i < 4; ++i) {
;         const int c = tid + 512 * i, row = c >> 4, ch = c & 15; const unsigned o = offb(row, ch);
;         const u32x4 kv = *(const u32x4*)(kp + (size_t)row * NIN + ch * 8), vv = *(const u32x4*)(kp + 512 + (size_t)row * NIN + ch * 8);
;         const u32x4 sf = *(const u32x4*)(sp + row * 128 + ch * 8), sb = *(const u32x4*)(sp + 16384 + row * 128 + ch * 8);
;         *(LAS u32x4*)(KT + o) = kv; *(LAS u32x4*)(VT + o) = vv; *(LAS u32x4*)(SF + o) = sf; *(LAS u32x4*)(SB + o) = sb;
;     }
;     const int r32 = lane & 31, hi = lane >> 5, g1 = (lane >> 4) & 1, q4 = (lane & 15) >> 2, p4 = lane & 3;
;     const int cb = wid & 3, eh = wid >> 2;
;     const int cl = 32 * cb + r32;
;     const size_t tok = (size_t)b * SEQ + n * 128 + cl;
;     bf16x8 qf[8];
; #pragma unroll
;     for (int kd = 0; kd < 8; ++kd) qf[kd] = *(const bf16x8*)(P + tok * NIN + h * 128 + 16 * kd + 8 * hi);
;     __syncthreads();
;     f32x16 O[2], XF[2], XB[2];
; #pragma unroll
;     for (int e = 0; e < 2; ++e)
; #pragma unroll
;         for (int r = 0; r < 16; ++r) { O[e][r] = 0.f; XF[e][r] = 0.f; XB[e][r] = 0.f; }
;     float ff[16], fb[16];
; #pragma unroll
;     for (int r = 0; r < 16; ++r) { ff[r] = __builtin_amdgcn_exp2f((float)(31 - crow(r, hi)) * lgf2); fb[r] = __builtin_amdgcn_exp2f((float)crow(r, hi) * lgb2); }
	v_mul_f32_e32 v8, 0xbfb8aa3b, v70
	v_fma_f32 v9, v70, s3, -v8
	v_rndne_f32_e32 v62, v8
	v_fmac_f32_e32 v9, 0xb2a5705f, v70
	v_sub_f32_e32 v8, v8, v62
	v_add_f32_e32 v8, v8, v9
	v_exp_f32_e32 v76, v8
	v_lshlrev_b32_e32 v8, 7, v74
	v_ashrrev_i32_e32 v9, 31, v8
	v_lshlrev_b64 v[8:9], 1, v[8:9]
	v_lshl_add_u64 v[10:11], v[10:11], 0, v[8:9]
	v_cvt_i32_f32_e32 v77, v62
	v_lshl_add_u64 v[8:9], v[60:61], 0, v[8:9]
	global_load_dwordx4 v[60:63], v[10:11], off
	global_load_dwordx4 v[64:67], v[8:9], off
	s_mov_b32 s3, 0x7f800000
	v_cmp_neq_f32_e32 vcc, s3, v71
	v_ldexp_f32 v9, v76, v77
	s_nop 0
	v_cndmask_b32_e32 v8, v134, v75, vcc
	v_cmp_lt_f32_e64 vcc, |v71|, s0
	s_nop 1
	v_cndmask_b32_e32 v8, v8, v71, vcc
	v_cmp_nlt_f32_e32 vcc, s6, v70
	v_mul_f32_e32 v138, 0xbfb8aa3b, v8
	v_bfe_u32 v8, v131, 2, 2
	v_cndmask_b32_e32 v9, 0, v9, vcc
	v_cmp_ngt_f32_e32 vcc, s7, v70
	v_lshlrev_b32_e32 v70, 2, v69
	v_and_b32_e32 v70, 12, v70
	v_cndmask_b32_e32 v9, v134, v9, vcc
	v_add_f32_e32 v11, 1.0, v9
	v_frexp_mant_f32_e32 v10, v11
	v_cmp_gt_f32_e64 s[8:9], s8, v10
	v_lshlrev_b32_e32 v10, 8, v69
	v_bfe_u32 v69, v69, 2, 2
	v_bitop3_b32 v69, v70, v68, v69 bitop3:0x36
	v_lshl_or_b32 v10, v69, 4, v10
	v_add_u32_e32 v69, s70, v10
	s_waitcnt vmcnt(15)
	ds_write_b128 v69, v[0:3]
	s_waitcnt vmcnt(14)
	ds_write_b128 v69, v[4:7] offset:32768
	v_add_u32_e32 v0, s74, v10
	v_lshlrev_b32_e32 v1, 2, v72
	v_and_b32_e32 v1, 12, v1
	v_bfe_u32 v2, v72, 2, 2
	v_bitop3_b32 v1, v1, v68, v2 bitop3:0x36
	v_bfe_u32 v2, v73, 2, 2
	v_cmp_neq_f32_e64 s[4:5], s3, v9
	s_ashr_i32 s3, s2, 31
	s_lshl_b64 s[2:3], s[2:3], 11
	s_or_b32 s2, s2, s10
	s_waitcnt vmcnt(13)
	ds_write_b128 v0, v[12:15]
	v_add_u32_e32 v0, s75, v10
	v_and_b32_e32 v10, 31, v131
	s_waitcnt vmcnt(12)
	ds_write_b128 v0, v[16:19]
	v_lshlrev_b32_e32 v0, 8, v72
	v_lshl_or_b32 v0, v1, 4, v0
	v_add_u32_e32 v1, s70, v0
	s_waitcnt vmcnt(11)
	ds_write_b128 v1, v[20:23]
	s_waitcnt vmcnt(10)
	ds_write_b128 v1, v[24:27] offset:32768
	v_add_u32_e32 v1, s74, v0
	s_waitcnt vmcnt(9)
	ds_write_b128 v1, v[28:31]
	v_lshlrev_b32_e32 v1, 2, v73
	v_add_u32_e32 v0, s75, v0
	v_and_b32_e32 v1, 12, v1
	s_waitcnt vmcnt(8)
	ds_write_b128 v0, v[32:35]
	v_lshlrev_b32_e32 v0, 8, v73
	v_bitop3_b32 v1, v1, v68, v2 bitop3:0x36
	v_lshl_or_b32 v0, v1, 4, v0
	v_add_u32_e32 v1, s70, v0
	s_waitcnt vmcnt(7)
	ds_write_b128 v1, v[36:39]
	s_waitcnt vmcnt(6)
	ds_write_b128 v1, v[40:43] offset:32768
	v_add_u32_e32 v1, s74, v0
	s_waitcnt vmcnt(5)
	ds_write_b128 v1, v[44:47]
	v_lshlrev_b32_e32 v1, 2, v74
	v_add_u32_e32 v0, s75, v0
	v_and_b32_e32 v1, 12, v1
	v_bfe_u32 v2, v74, 2, 2
	s_waitcnt vmcnt(4)
	ds_write_b128 v0, v[48:51]
	v_lshlrev_b32_e32 v0, 8, v74
	v_bitop3_b32 v1, v1, v68, v2 bitop3:0x36
	v_lshl_or_b32 v2, v1, 4, v0
	v_add_u32_e32 v0, s70, v2
	v_or_b32_e32 v124, s76, v10
	s_waitcnt vmcnt(3)
	ds_write_b128 v0, v[52:55]
	s_waitcnt vmcnt(2)
	ds_write_b128 v0, v[56:59] offset:32768
	v_or_b32_e32 v0, s2, v124
	v_mad_u64_u32 v[0:1], s[10:11], v0, s1, v[126:127]
	v_mad_i32_i24 v1, s3, v136, v1
	v_lshl_add_u64 v[132:133], v[0:1], 0, s[52:53]
	v_lshl_add_u64 v[0:1], v[128:129], 1, v[132:133]
	global_load_dwordx4 v[48:51], v[0:1], off
	v_add_u32_e32 v3, s74, v2
	v_add_u32_e32 v2, s75, v2
	s_waitcnt vmcnt(2)
	ds_write_b128 v3, v[60:63]
	s_waitcnt vmcnt(1)
	ds_write_b128 v2, v[64:67]
	global_load_dwordx4 v[120:123], v[0:1], off offset:32
	global_load_dwordx4 v[116:119], v[0:1], off offset:64
	global_load_dwordx4 v[112:115], v[0:1], off offset:96
	global_load_dwordx4 v[108:111], v[0:1], off offset:128
	global_load_dwordx4 v[104:107], v[0:1], off offset:160
	global_load_dwordx4 v[100:103], v[0:1], off offset:192
	global_load_dwordx4 v[96:99], v[0:1], off offset:224
	v_sub_u32_e32 v0, 31, v130
	v_or_b32_e32 v40, 1, v130
	v_cvt_f32_i32_e32 v0, v0
	v_sub_u32_e32 v1, 31, v40
	v_cvt_f32_i32_e32 v1, v1
	v_or_b32_e32 v41, 2, v130
	v_mul_f32_e32 v0, v138, v0
	v_exp_f32_e32 v52, v0
	v_mul_f32_e32 v0, v138, v1
	v_sub_u32_e32 v1, 31, v41
	v_or_b32_e32 v69, 3, v130
	v_cvt_f32_i32_e32 v1, v1
	v_sub_u32_e32 v2, 31, v69
	v_cvt_f32_i32_e32 v2, v2
	v_exp_f32_e32 v53, v0
	v_mul_f32_e32 v0, v138, v1
	v_sub_u32_e32 v1, 23, v130
	v_exp_f32_e32 v54, v0
	v_mul_f32_e32 v0, v138, v2
	v_cvt_f32_i32_e32 v1, v1
	v_sub_u32_e32 v2, 22, v130
	v_cvt_f32_i32_e32 v2, v2
	v_exp_f32_e32 v55, v0
	v_mul_f32_e32 v0, v138, v1
	v_sub_u32_e32 v1, 21, v130
	v_exp_f32_e32 v56, v0
	v_mul_f32_e32 v0, v138, v2
	v_cvt_f32_i32_e32 v1, v1
	v_sub_u32_e32 v2, 20, v130
	v_cvt_f32_i32_e32 v2, v2
	v_exp_f32_e32 v57, v0
	v_mul_f32_e32 v0, v138, v1
	v_sub_u32_e32 v1, 15, v130
	v_exp_f32_e32 v58, v0
	v_mul_f32_e32 v0, v138, v2
	v_cvt_f32_i32_e32 v1, v1
	v_sub_u32_e32 v2, 14, v130
	v_cvt_f32_i32_e32 v2, v2
	v_exp_f32_e32 v59, v0
	v_mul_f32_e32 v0, v138, v1
	v_exp_f32_e32 v60, v0
	v_mul_f32_e32 v0, v138, v2
	v_exp_f32_e32 v61, v0
	v_sub_u32_e32 v0, 13, v130
	v_cvt_f32_i32_e32 v4, v0
	v_sub_u32_e32 v0, 12, v130
	v_cvt_f32_i32_e32 v5, v0
	v_lshlrev_b32_e32 v0, 2, v131
	v_and_b32_e32 v12, 12, v0
	v_lshlrev_b32_e32 v0, 8, v131
	v_and_b32_e32 v13, 0x1f00, v0
	v_bitop3_b32 v0, v12, v94, v8 bitop3:0x36
	v_lshl_add_u32 v0, v0, 4, v13
	v_add_u32_e32 v140, s70, v0
	s_waitcnt lgkmcnt(0)
	s_barrier
; #define LAS __attribute__((address_space(3)))
; __device__ __forceinline__ void r2_unit(const Args& a, unsigned char* ws, bf16* STB, LAS unsigned char* lds, int l, int unit, int tid, int wid, int lane, int dry) {
;     ...
;     for (int mb = 0; mb < 4; ++mb) {
;         f32x16 S;
; #pragma unroll
;         for (int r = 0; r < 16; ++r) S[r] = 0.f;
; #pragma unroll
;         for (int kd = 0; kd < 8; ++kd) { const bf16x8 kf = *(const LAS bf16x8*)(KT + kb[kd] + 8192 * mb); S = __builtin_amdgcn_mfma_f32_32x32x16_bf16(kf, qf[kd], S, 0, 0, 0); }
;         if (mb < cb) { const float fa = __builtin_amdgcn_exp2f((float)(cl - 32 * mb - 31) * lgf2);
; #pragma unroll
;             for (int r = 0; r < 16; ++r) S[r] *= fa * ff[r];
;         } else if (mb > cb) { const float fa = __builtin_amdgcn_exp2f((float)(32 * mb - cl) * lgb2);
; #pragma unroll
;             for (int r = 0; r < 16; ++r) S[r] *= fa * fb[r];
	ds_read_b128 v[0:3], v140
	v_mul_f32_e32 v4, v138, v4
	v_exp_f32_e32 v62, v4
	v_add_u32_e32 v4, 2, v94
	v_bitop3_b32 v4, v12, v4, v8 bitop3:0x36
	v_lshl_add_u32 v4, v4, 4, v13
	v_add_u32_e32 v141, s70, v4
	v_mul_f32_e32 v14, v138, v5
	ds_read_b128 v[4:7], v141
	s_waitcnt vmcnt(7) lgkmcnt(1)
	v_mfma_f32_32x32x16_bf16 v[18:33], v[0:3], v[48:51], 0
	v_sub_u32_e32 v0, 7, v130
	v_cvt_f32_i32_e32 v15, v0
	v_add_u32_e32 v0, 4, v94
	v_bitop3_b32 v0, v12, v0, v8 bitop3:0x36
	v_lshl_add_u32 v0, v0, 4, v13
	v_add_u32_e32 v143, s70, v0
	ds_read_b128 v[0:3], v143
	s_waitcnt vmcnt(6) lgkmcnt(1)
	v_mfma_f32_32x32x16_bf16 v[18:33], v[4:7], v[120:123], v[18:33]
	v_add_u32_e32 v4, 6, v94
	v_bitop3_b32 v4, v12, v4, v8 bitop3:0x36
	v_lshl_add_u32 v4, v4, 4, v13
	v_add_u32_e32 v144, s70, v4
	ds_read_b128 v[4:7], v144
	v_exp_f32_e32 v63, v14
	v_mul_f32_e32 v14, v138, v15
	s_waitcnt vmcnt(5) lgkmcnt(1)
	v_mfma_f32_32x32x16_bf16 v[18:33], v[0:3], v[116:119], v[18:33]
	v_sub_u32_e32 v0, 6, v130
	v_cvt_f32_i32_e32 v15, v0
	v_add_u32_e32 v0, 8, v94
	v_bitop3_b32 v0, v12, v0, v8 bitop3:0x36
	v_lshl_add_u32 v0, v0, 4, v13
	v_add_u32_e32 v146, s70, v0
	ds_read_b128 v[0:3], v146
	s_waitcnt vmcnt(4) lgkmcnt(1)
	v_mfma_f32_32x32x16_bf16 v[18:33], v[4:7], v[112:115], v[18:33]
	v_add_u32_e32 v4, 10, v94
	v_bitop3_b32 v4, v12, v4, v8 bitop3:0x36
	v_lshl_add_u32 v4, v4, 4, v13
	v_add_u32_e32 v148, s70, v4
	ds_read_b128 v[4:7], v148
	v_exp_f32_e32 v64, v14
	v_mul_f32_e32 v14, v138, v15
	s_waitcnt vmcnt(3) lgkmcnt(1)
	v_mfma_f32_32x32x16_bf16 v[18:33], v[0:3], v[108:111], v[18:33]
	v_sub_u32_e32 v0, 5, v130
	v_cvt_f32_i32_e32 v15, v0
	v_add_u32_e32 v0, 12, v94
	v_bitop3_b32 v0, v12, v0, v8 bitop3:0x36
	v_lshl_add_u32 v0, v0, 4, v13
	v_add_u32_e32 v150, s70, v0
	ds_read_b128 v[0:3], v150
	s_waitcnt vmcnt(2) lgkmcnt(1)
	v_mfma_f32_32x32x16_bf16 v[18:33], v[4:7], v[104:107], v[18:33]
	v_sub_u32_e32 v4, 4, v130
	v_cvt_f32_i32_e32 v16, v4
	v_add_u32_e32 v4, 14, v94
	v_bitop3_b32 v4, v12, v4, v8 bitop3:0x36
	v_lshl_add_u32 v4, v4, 4, v13
	v_add_u32_e32 v153, s70, v4
	ds_read_b128 v[4:7], v153
	s_waitcnt vmcnt(1) lgkmcnt(1)
	v_mfma_f32_32x32x16_bf16 v[18:33], v[0:3], v[100:103], v[18:33]
	v_mul_f32_e32 v0, v138, v15
	v_exp_f32_e32 v180, v0
	v_mul_f32_e32 v0, v138, v16
	v_exp_f32_e32 v65, v14
	v_exp_f32_e32 v181, v0
	v_cmp_lt_f32_e64 s[6:7], |v9|, s0
	v_cmp_ne_u32_e64 s[2:3], 1, v137
	s_waitcnt vmcnt(0) lgkmcnt(0)
	v_mfma_f32_32x32x16_bf16 v[18:33], v[4:7], v[96:99], v[18:33]
	s_andn2_b64 vcc, exec, s[54:55]
	s_cbranch_vccnz .LBB0_1394
	v_subrev_u32_e32 v0, 31, v124
	v_cvt_f32_i32_e32 v0, v0
	s_mov_b64 s[10:11], 0
	v_mul_f32_e32 v0, v138, v0
	v_exp_f32_e32 v12, v0
	s_nop 0
	v_pk_mul_f32 v[14:15], v[12:13], v[60:61] op_sel_hi:[0,1]
	s_nop 2
	v_pk_mul_f32 v[34:35], v[26:27], v[14:15]
	v_pk_mul_f32 v[14:15], v[12:13], v[62:63] op_sel_hi:[0,1]
	v_pk_mul_f32 v[0:1], v[12:13], v[52:53] op_sel_hi:[0,1]
	v_pk_mul_f32 v[2:3], v[12:13], v[54:55] op_sel_hi:[0,1]
	v_pk_mul_f32 v[4:5], v[12:13], v[56:57] op_sel_hi:[0,1]
	v_pk_mul_f32 v[6:7], v[12:13], v[58:59] op_sel_hi:[0,1]
	v_pk_mul_f32 v[36:37], v[28:29], v[14:15]
	v_pk_mul_f32 v[14:15], v[12:13], v[64:65] op_sel_hi:[0,1]
	v_mul_f32_e32 v13, v12, v180
	v_pk_mul_f32 v[0:1], v[18:19], v[0:1]
	v_pk_mul_f32 v[2:3], v[20:21], v[2:3]
	v_pk_mul_f32 v[4:5], v[22:23], v[4:5]
	v_pk_mul_f32 v[6:7], v[24:25], v[6:7]
	v_pk_mul_f32 v[38:39], v[30:31], v[14:15]
	v_mul_f32_e32 v42, v32, v13
	v_mul_f32_e32 v43, v12, v181
	s_branch .LBB0_1395
